# GEMM K-loops: LDS-DMA loads use the SGPR-base form, 64-bit VALU address adds removed from the load segments
# baseline (speedup 1.0000x reference)
; #define PG8_STAGE(bufoff, gbase, voff) do { _Pragma("unroll") for (int _i = 0; _i < 2; ++_i) \
;         __builtin_amdgcn_global_load_lds((const unsigned*)((const char*)(gbase) + (voff)[_i]), (LAS unsigned*)(lds + (bufoff) + ldsw + _i * 8192), 16, 0, 0); } while (0)
; #define PG8_LDA(dst, b, h) do { _Pragma("unroll") for (int m = 0; m < 4; ++m) _Pragma("unroll") for (int k = 0; k < 2; ++k) dst[m][k] = *(const LAS bf16x8*)(lds + PG8_SA(b, h) + aoff + m * 2048 + k * 1024); } while (0)
; #define PG8_LDB(dst, b, h) do { _Pragma("unroll") for (int n = 0; n < 2; ++n) _Pragma("unroll") for (int k = 0; k < 2; ++k) dst[n][k] = *(const LAS bf16x8*)(lds + PG8_SB(b, h) + boff + n * 2048 + k * 1024); } while (0)
; #define PG8_WAIT_V(n) asm volatile("s_waitcnt vmcnt(" #n ")" ::: "memory")
; #define PG8_WAIT_L(n) asm volatile("s_waitcnt lgkmcnt(" #n ")" ::: "memory")
; template <class Epi, bool ALIGN_EPI>
; __device__ __forceinline__ void gemm_phase(LAS unsigned char* lds, const int tid, const Gemm g, const StaticOrder& S, const Epi& E) {
;     ...
;             const bool last = (t == nt - 2);
;             const char* a1 = cA + (size_t)(t + 1) * kstepA;
;             const char* a2 = last ? nA : cA + (size_t)(t + 2) * kstepA; const char* b2 = last ? nB : cB + (size_t)(t + 2) * kstepB;
;             const char* a3 = a2 + kstepA; const char* b3 = b2 + kstepB;
;             PG8_LDB(B0, 0, 0); PG8_LDB(B1, 0, 1); PG8_SCHED; PG8_LDA(At, 0, 0); PG8_STAGE(PG8_SA(1, 1), a1 + hstepA, voffA);
;             PG8_WAIT_V(8); PG8_WAIT_L(0); PG8_BAR; PG8_MMA(0, 0, At, B0); PG8_MMA(0, 1, At, B1); PG8_BAR; PG8_SCHED;
;             PG8_LDA(At, 0, 1); PG8_STAGE(PG8_SB(0, 0), b2, voffB); PG8_STAGE(PG8_SB(0, 1), b2 + hstepB, voffB); PG8_STAGE(PG8_SA(0, 0), a2, voffA);
;             PG8_WAIT_V(8); PG8_WAIT_L(0); PG8_BAR; PG8_MMA(1, 0, At, B0); PG8_MMA(1, 1, At, B1); PG8_BAR; PG8_SCHED;
;             PG8_LDB(B0, 1, 0); PG8_LDB(B1, 1, 1); PG8_SCHED; PG8_LDA(At, 1, 0); PG8_STAGE(PG8_SA(0, 1), a2 + hstepA, voffA);
;             PG8_WAIT_V(8); PG8_WAIT_L(0); PG8_BAR; PG8_MMA(0, 0, At, B0); PG8_MMA(0, 1, At, B1); PG8_BAR; PG8_SCHED;
;             PG8_LDA(At, 1, 1); PG8_STAGE(PG8_SB(1, 0), b3, voffB); PG8_STAGE(PG8_SB(1, 1), b3 + hstepB, voffB); PG8_STAGE(PG8_SA(1, 0), a3, voffA);
;             PG8_WAIT_V(8); PG8_WAIT_L(0); PG8_BAR; PG8_MMA(1, 0, At, B0); PG8_MMA(1, 1, At, B1); PG8_BAR; PG8_SCHED;
.LBB0_113:
	s_add_i32 s90, s90, 2
	s_and_b64 s[34:35], exec, s[34:35]
	s_cselect_b32 s55, s23, s27
	s_cselect_b32 s54, s22, s25
	s_add_u32 s34, s92, 0x120000
	s_addc_u32 s35, s93, 0
	s_add_i32 s91, 0, 0x10000
	s_add_i32 s96, 0, 0x14000
	v_add_u32_e32 v148, s91, v175
	v_add_u32_e32 v164, s96, v175
	ds_read_b128 v[136:139], v148
	ds_read_b128 v[140:143], v148 offset:1024
	ds_read_b128 v[144:147], v148 offset:2048
	ds_read_b128 v[148:151], v148 offset:3072
	ds_read_b128 v[152:155], v164
	ds_read_b128 v[156:159], v164 offset:1024
	ds_read_b128 v[160:163], v164 offset:2048
	ds_read_b128 v[164:167], v164 offset:3072
	s_add_i32 m0, s56, 0xc000
	ds_read_b128 v[168:171], v177
	ds_read_b128 v[178:181], v177 offset:1024
	ds_read_b128 v[182:185], v177 offset:2048
	ds_read_b128 v[186:189], v177 offset:3072
	ds_read_b128 v[190:193], v177 offset:4096
	ds_read_b128 v[210:213], v177 offset:5120
	ds_read_b128 v[214:217], v177 offset:6144
	ds_read_b128 v[218:221], v177 offset:7168
	global_load_lds_dwordx4 v134, s[30:31]
	s_add_i32 m0, s56, 0xe000
	s_nop 0
	global_load_lds_dwordx4 v132, s[30:31]
	s_sub_u32 s98, s30, 0x4000
	s_subb_u32 s99, s31, 0
	s_mov_b32 m0, s70
	s_nop 0
	global_load_lds_dwordx4 v134, s[98:99]
	s_mov_b32 m0, s71
	s_nop 0
	global_load_lds_dwordx4 v132, s[98:99]
	s_waitcnt vmcnt(8)
	s_waitcnt lgkmcnt(0)
	s_barrier
	s_waitcnt lgkmcnt(0)
	v_mfma_f32_16x16x32_bf16 v[126:129], v[136:139], v[168:171], v[126:129]
	v_mfma_f32_16x16x32_bf16 v[94:97], v[144:147], v[168:171], v[94:97]
	v_mfma_f32_16x16x32_bf16 v[122:125], v[136:139], v[182:185], v[122:125]
	v_mfma_f32_16x16x32_bf16 v[90:93], v[144:147], v[182:185], v[90:93]
	v_mfma_f32_16x16x32_bf16 v[118:121], v[136:139], v[190:193], v[118:121]
	v_mfma_f32_16x16x32_bf16 v[86:89], v[144:147], v[190:193], v[86:89]
	v_mfma_f32_16x16x32_bf16 v[114:117], v[136:139], v[214:217], v[114:117]
	v_mfma_f32_16x16x32_bf16 v[82:85], v[144:147], v[214:217], v[82:85]
	v_mfma_f32_16x16x32_bf16 v[126:129], v[140:143], v[178:181], v[126:129]
	v_mfma_f32_16x16x32_bf16 v[94:97], v[148:151], v[178:181], v[94:97]
	v_mfma_f32_16x16x32_bf16 v[122:125], v[140:143], v[186:189], v[122:125]
	v_mfma_f32_16x16x32_bf16 v[90:93], v[148:151], v[186:189], v[90:93]
	v_mfma_f32_16x16x32_bf16 v[118:121], v[140:143], v[210:213], v[118:121]
	v_mfma_f32_16x16x32_bf16 v[86:89], v[148:151], v[210:213], v[86:89]
	v_mfma_f32_16x16x32_bf16 v[114:117], v[140:143], v[218:221], v[114:117]
	v_mfma_f32_16x16x32_bf16 v[82:85], v[148:151], v[218:221], v[82:85]
	v_mfma_f32_16x16x32_bf16 v[62:65], v[152:155], v[168:171], v[62:65]
	v_mfma_f32_16x16x32_bf16 v[38:41], v[160:163], v[168:171], v[38:41]
	v_mfma_f32_16x16x32_bf16 v[58:61], v[152:155], v[182:185], v[58:61]
	v_mfma_f32_16x16x32_bf16 v[30:33], v[160:163], v[182:185], v[30:33]
	v_mfma_f32_16x16x32_bf16 v[54:57], v[152:155], v[190:193], v[54:57]
	v_mfma_f32_16x16x32_bf16 v[22:25], v[160:163], v[190:193], v[22:25]
	v_mfma_f32_16x16x32_bf16 v[50:53], v[152:155], v[214:217], v[50:53]
	v_mfma_f32_16x16x32_bf16 v[18:21], v[160:163], v[214:217], v[18:21]
	v_mfma_f32_16x16x32_bf16 v[62:65], v[156:159], v[178:181], v[62:65]
	v_mfma_f32_16x16x32_bf16 v[38:41], v[164:167], v[178:181], v[38:41]
	v_mfma_f32_16x16x32_bf16 v[58:61], v[156:159], v[186:189], v[58:61]
	v_mfma_f32_16x16x32_bf16 v[30:33], v[164:167], v[186:189], v[30:33]
	v_mfma_f32_16x16x32_bf16 v[54:57], v[156:159], v[210:213], v[54:57]
	v_mfma_f32_16x16x32_bf16 v[22:25], v[164:167], v[210:213], v[22:25]
	v_mfma_f32_16x16x32_bf16 v[50:53], v[156:159], v[218:221], v[50:53]
	v_mfma_f32_16x16x32_bf16 v[18:21], v[164:167], v[218:221], v[18:21]
	s_barrier
	s_add_i32 s91, s91, s29
	s_mov_b32 m0, s91
	ds_read_b128 v[168:171], v177 offset:16384
	ds_read_b128 v[178:181], v177 offset:17408
	ds_read_b128 v[182:185], v177 offset:18432
	ds_read_b128 v[186:189], v177 offset:19456
	ds_read_b128 v[190:193], v177 offset:20480
	ds_read_b128 v[210:213], v177 offset:21504
	ds_read_b128 v[214:217], v177 offset:22528
	ds_read_b128 v[218:221], v177 offset:23552
	global_load_lds_dwordx4 v0, s[54:55]
	s_add_i32 m0, s91, 0x2000
	s_add_u32 s94, s54, 0x4000
	s_addc_u32 s95, s55, 0
	s_add_i32 s91, s96, s29
	global_load_lds_dwordx4 v130, s[54:55]
	s_mov_b32 m0, s91
	s_nop 0
	global_load_lds_dwordx4 v0, s[94:95]
	s_add_i32 m0, s91, 0x2000
	s_nop 0
	global_load_lds_dwordx4 v130, s[94:95]
	s_waitcnt vmcnt(4)
	s_waitcnt lgkmcnt(0)
	s_barrier
	s_waitcnt lgkmcnt(0)
	v_mfma_f32_16x16x32_bf16 v[110:113], v[136:139], v[168:171], v[110:113]
	v_mfma_f32_16x16x32_bf16 v[78:81], v[144:147], v[168:171], v[78:81]
	v_mfma_f32_16x16x32_bf16 v[106:109], v[136:139], v[182:185], v[106:109]
	v_mfma_f32_16x16x32_bf16 v[74:77], v[144:147], v[182:185], v[74:77]
	v_mfma_f32_16x16x32_bf16 v[102:105], v[136:139], v[190:193], v[102:105]
	v_mfma_f32_16x16x32_bf16 v[70:73], v[144:147], v[190:193], v[70:73]
	v_mfma_f32_16x16x32_bf16 v[98:101], v[136:139], v[214:217], v[98:101]
	v_mfma_f32_16x16x32_bf16 v[66:69], v[144:147], v[214:217], v[66:69]
	v_mfma_f32_16x16x32_bf16 v[110:113], v[140:143], v[178:181], v[110:113]
	v_mfma_f32_16x16x32_bf16 v[78:81], v[148:151], v[178:181], v[78:81]
	v_mfma_f32_16x16x32_bf16 v[106:109], v[140:143], v[186:189], v[106:109]
	v_mfma_f32_16x16x32_bf16 v[74:77], v[148:151], v[186:189], v[74:77]
	v_mfma_f32_16x16x32_bf16 v[102:105], v[140:143], v[210:213], v[102:105]
	v_mfma_f32_16x16x32_bf16 v[70:73], v[148:151], v[210:213], v[70:73]
	v_mfma_f32_16x16x32_bf16 v[98:101], v[140:143], v[218:221], v[98:101]
	v_mfma_f32_16x16x32_bf16 v[66:69], v[148:151], v[218:221], v[66:69]
	v_mfma_f32_16x16x32_bf16 v[46:49], v[152:155], v[168:171], v[46:49]
	v_mfma_f32_16x16x32_bf16 v[14:17], v[160:163], v[168:171], v[14:17]
	v_mfma_f32_16x16x32_bf16 v[42:45], v[152:155], v[182:185], v[42:45]
	v_mfma_f32_16x16x32_bf16 v[10:13], v[160:163], v[182:185], v[10:13]
	v_mfma_f32_16x16x32_bf16 v[34:37], v[152:155], v[190:193], v[34:37]
	v_mfma_f32_16x16x32_bf16 v[6:9], v[160:163], v[190:193], v[6:9]
	v_mfma_f32_16x16x32_bf16 v[26:29], v[152:155], v[214:217], v[26:29]
	v_mfma_f32_16x16x32_bf16 v[2:5], v[160:163], v[214:217], v[2:5]
	v_mfma_f32_16x16x32_bf16 v[46:49], v[156:159], v[178:181], v[46:49]
	v_mfma_f32_16x16x32_bf16 v[14:17], v[164:167], v[178:181], v[14:17]
	v_mfma_f32_16x16x32_bf16 v[42:45], v[156:159], v[186:189], v[42:45]
	v_mfma_f32_16x16x32_bf16 v[10:13], v[164:167], v[186:189], v[10:13]
	v_mfma_f32_16x16x32_bf16 v[34:37], v[156:159], v[210:213], v[34:37]
	v_mfma_f32_16x16x32_bf16 v[6:9], v[164:167], v[210:213], v[6:9]
	v_mfma_f32_16x16x32_bf16 v[26:29], v[156:159], v[218:221], v[26:29]
	v_mfma_f32_16x16x32_bf16 v[2:5], v[164:167], v[218:221], v[2:5]
	s_barrier
; #define PG8_STAGE(bufoff, gbase, voff) do { _Pragma("unroll") for (int _i = 0; _i < 2; ++_i) \
;         __builtin_amdgcn_global_load_lds((const unsigned*)((const char*)(gbase) + (voff)[_i]), (LAS unsigned*)(lds + (bufoff) + ldsw + _i * 8192), 16, 0, 0); } while (0)
; #define PG8_LDA(dst, b, h) do { _Pragma("unroll") for (int m = 0; m < 4; ++m) _Pragma("unroll") for (int k = 0; k < 2; ++k) dst[m][k] = *(const LAS bf16x8*)(lds + PG8_SA(b, h) + aoff + m * 2048 + k * 1024); } while (0)
; #define PG8_LDB(dst, b, h) do { _Pragma("unroll") for (int n = 0; n < 2; ++n) _Pragma("unroll") for (int k = 0; k < 2; ++k) dst[n][k] = *(const LAS bf16x8*)(lds + PG8_SB(b, h) + boff + n * 2048 + k * 1024); } while (0)
; #define PG8_MMA(ai, bj, At, Bt) do { __builtin_amdgcn_s_setprio(1); _Pragma("unroll") for (int m = 0; m < 4; ++m) _Pragma("unroll") for (int n = 0; n < 2; ++n) _Pragma("unroll") for (int k = 0; k < 2; ++k) \
;         acc[ai][bj][m][n] = __builtin_amdgcn_mfma_f32_16x16x32_bf16(Bt[n][k], At[m][k], acc[ai][bj][m][n], 0, 0, 0); __builtin_amdgcn_s_setprio(0); } while (0)
; #define PG8_WAIT_V(n) asm volatile("s_waitcnt vmcnt(" #n ")" ::: "memory")
; #define PG8_WAIT_L(n) asm volatile("s_waitcnt lgkmcnt(" #n ")" ::: "memory")
; #define PG8_BAR __builtin_amdgcn_s_barrier()
; template <class Epi, bool ALIGN_EPI>
; __device__ __forceinline__ void gemm_phase(LAS unsigned char* lds, const int tid, const Gemm g, const StaticOrder& S, const Epi& E) {
;     ...
;             PG8_WAIT_V(8); PG8_WAIT_L(0); PG8_BAR; PG8_MMA(0, 0, At, B0); PG8_MMA(0, 1, At, B1); PG8_BAR; PG8_SCHED;
;             PG8_LDA(At, 0, 1); PG8_STAGE(PG8_SB(0, 0), b2, voffB); PG8_STAGE(PG8_SB(0, 1), b2 + hstepB, voffB); PG8_STAGE(PG8_SA(0, 0), a2, voffA);
;             PG8_WAIT_V(8); PG8_WAIT_L(0); PG8_BAR; PG8_MMA(1, 0, At, B0); PG8_MMA(1, 1, At, B1); PG8_BAR; PG8_SCHED;
;             PG8_LDB(B0, 1, 0); PG8_LDB(B1, 1, 1); PG8_SCHED; PG8_LDA(At, 1, 0); PG8_STAGE(PG8_SA(0, 1), a2 + hstepA, voffA);
;             PG8_WAIT_V(8); PG8_WAIT_L(0); PG8_BAR; PG8_MMA(0, 0, At, B0); PG8_MMA(0, 1, At, B1); PG8_BAR; PG8_SCHED;
;             PG8_LDA(At, 1, 1); PG8_STAGE(PG8_SB(1, 0), b3, voffB); PG8_STAGE(PG8_SB(1, 1), b3 + hstepB, voffB); PG8_STAGE(PG8_SA(1, 0), a3, voffA);
;             PG8_WAIT_V(8); PG8_WAIT_L(0); PG8_BAR; PG8_MMA(1, 0, At, B0); PG8_MMA(1, 1, At, B1); PG8_BAR; PG8_SCHED;
;         }
	s_add_i32 s91, 0, 0x18000
	s_add_i32 s94, 0, 0x1c000
	v_add_u32_e32 v148, s91, v175
	v_add_u32_e32 v164, s94, v175
	ds_read_b128 v[136:139], v148
	ds_read_b128 v[140:143], v148 offset:1024
	ds_read_b128 v[144:147], v148 offset:2048
	ds_read_b128 v[148:151], v148 offset:3072
	ds_read_b128 v[152:155], v164
	ds_read_b128 v[156:159], v164 offset:1024
	ds_read_b128 v[160:163], v164 offset:2048
	ds_read_b128 v[164:167], v164 offset:3072
	s_mov_b32 m0, s56
	s_nop 0
	global_load_lds_dwordx4 v0, s[92:93]
	s_mov_b32 m0, s58
	s_nop 0
	global_load_lds_dwordx4 v130, s[92:93]
	s_add_u32 s92, s92, 0x4000
	s_addc_u32 s93, s93, 0
	s_mov_b32 m0, s63
	ds_read_b128 v[168:171], v177 offset:32768
	ds_read_b128 v[178:181], v177 offset:33792
	ds_read_b128 v[182:185], v177 offset:34816
	ds_read_b128 v[186:189], v177 offset:35840
	ds_read_b128 v[190:193], v177 offset:36864
	ds_read_b128 v[210:213], v177 offset:37888
	ds_read_b128 v[214:217], v177 offset:38912
	ds_read_b128 v[218:221], v177 offset:39936
	global_load_lds_dwordx4 v0, s[92:93]
	s_mov_b32 m0, s64
	s_nop 0
	global_load_lds_dwordx4 v130, s[92:93]
	s_waitcnt vmcnt(8)
	s_waitcnt lgkmcnt(0)
	s_barrier
	s_waitcnt lgkmcnt(0)
	v_mfma_f32_16x16x32_bf16 v[126:129], v[136:139], v[168:171], v[126:129]
	v_mfma_f32_16x16x32_bf16 v[94:97], v[144:147], v[168:171], v[94:97]
	v_mfma_f32_16x16x32_bf16 v[122:125], v[136:139], v[182:185], v[122:125]
	v_mfma_f32_16x16x32_bf16 v[90:93], v[144:147], v[182:185], v[90:93]
	v_mfma_f32_16x16x32_bf16 v[118:121], v[136:139], v[190:193], v[118:121]
	v_mfma_f32_16x16x32_bf16 v[86:89], v[144:147], v[190:193], v[86:89]
	v_mfma_f32_16x16x32_bf16 v[114:117], v[136:139], v[214:217], v[114:117]
	v_mfma_f32_16x16x32_bf16 v[82:85], v[144:147], v[214:217], v[82:85]
	v_mfma_f32_16x16x32_bf16 v[126:129], v[140:143], v[178:181], v[126:129]
	v_mfma_f32_16x16x32_bf16 v[94:97], v[148:151], v[178:181], v[94:97]
	v_mfma_f32_16x16x32_bf16 v[122:125], v[140:143], v[186:189], v[122:125]
	v_mfma_f32_16x16x32_bf16 v[90:93], v[148:151], v[186:189], v[90:93]
	v_mfma_f32_16x16x32_bf16 v[118:121], v[140:143], v[210:213], v[118:121]
	v_mfma_f32_16x16x32_bf16 v[86:89], v[148:151], v[210:213], v[86:89]
	v_mfma_f32_16x16x32_bf16 v[114:117], v[140:143], v[218:221], v[114:117]
	v_mfma_f32_16x16x32_bf16 v[82:85], v[148:151], v[218:221], v[82:85]
	v_mfma_f32_16x16x32_bf16 v[62:65], v[152:155], v[168:171], v[62:65]
	v_mfma_f32_16x16x32_bf16 v[38:41], v[160:163], v[168:171], v[38:41]
	v_mfma_f32_16x16x32_bf16 v[58:61], v[152:155], v[182:185], v[58:61]
	v_mfma_f32_16x16x32_bf16 v[30:33], v[160:163], v[182:185], v[30:33]
	v_mfma_f32_16x16x32_bf16 v[54:57], v[152:155], v[190:193], v[54:57]
	v_mfma_f32_16x16x32_bf16 v[22:25], v[160:163], v[190:193], v[22:25]
	v_mfma_f32_16x16x32_bf16 v[50:53], v[152:155], v[214:217], v[50:53]
	v_mfma_f32_16x16x32_bf16 v[18:21], v[160:163], v[214:217], v[18:21]
	v_mfma_f32_16x16x32_bf16 v[62:65], v[156:159], v[178:181], v[62:65]
	v_mfma_f32_16x16x32_bf16 v[38:41], v[164:167], v[178:181], v[38:41]
	v_mfma_f32_16x16x32_bf16 v[58:61], v[156:159], v[186:189], v[58:61]
	v_mfma_f32_16x16x32_bf16 v[30:33], v[164:167], v[186:189], v[30:33]
	v_mfma_f32_16x16x32_bf16 v[54:57], v[156:159], v[210:213], v[54:57]
	v_mfma_f32_16x16x32_bf16 v[22:25], v[164:167], v[210:213], v[22:25]
	v_mfma_f32_16x16x32_bf16 v[50:53], v[156:159], v[218:221], v[50:53]
	v_mfma_f32_16x16x32_bf16 v[18:21], v[164:167], v[218:221], v[18:21]
	s_barrier
	s_add_u32 s92, s54, 0x40000
	s_addc_u32 s93, s55, 0
	s_add_i32 s91, s91, s29
	s_mov_b32 m0, s91
	ds_read_b128 v[168:171], v177 offset:49152
	ds_read_b128 v[178:181], v177 offset:50176
	ds_read_b128 v[182:185], v177 offset:51200
	ds_read_b128 v[186:189], v177 offset:52224
	ds_read_b128 v[190:193], v177 offset:53248
	ds_read_b128 v[210:213], v177 offset:54272
	ds_read_b128 v[214:217], v177 offset:55296
	ds_read_b128 v[218:221], v177 offset:56320
	global_load_lds_dwordx4 v0, s[92:93]
	s_add_i32 m0, s91, 0x2000
	s_add_u32 s54, s54, 0x44000
	s_addc_u32 s55, s55, 0
	s_add_i32 s91, s94, s29
	global_load_lds_dwordx4 v130, s[92:93]
	s_mov_b32 m0, s91
	s_nop 0
	global_load_lds_dwordx4 v0, s[54:55]
	s_add_i32 m0, s91, 0x2000
	s_nop 0
	global_load_lds_dwordx4 v130, s[54:55]
	s_waitcnt vmcnt(4)
	s_waitcnt lgkmcnt(0)
	s_barrier
	s_waitcnt lgkmcnt(0)
	v_mfma_f32_16x16x32_bf16 v[110:113], v[136:139], v[168:171], v[110:113]
	v_mfma_f32_16x16x32_bf16 v[78:81], v[144:147], v[168:171], v[78:81]
	v_mfma_f32_16x16x32_bf16 v[106:109], v[136:139], v[182:185], v[106:109]
	v_mfma_f32_16x16x32_bf16 v[74:77], v[144:147], v[182:185], v[74:77]
	v_mfma_f32_16x16x32_bf16 v[102:105], v[136:139], v[190:193], v[102:105]
	v_mfma_f32_16x16x32_bf16 v[70:73], v[144:147], v[190:193], v[70:73]
	v_mfma_f32_16x16x32_bf16 v[98:101], v[136:139], v[214:217], v[98:101]
	v_mfma_f32_16x16x32_bf16 v[66:69], v[144:147], v[214:217], v[66:69]
	v_mfma_f32_16x16x32_bf16 v[110:113], v[140:143], v[178:181], v[110:113]
	v_mfma_f32_16x16x32_bf16 v[78:81], v[148:151], v[178:181], v[78:81]
	v_mfma_f32_16x16x32_bf16 v[106:109], v[140:143], v[186:189], v[106:109]
	v_mfma_f32_16x16x32_bf16 v[74:77], v[148:151], v[186:189], v[74:77]
	v_mfma_f32_16x16x32_bf16 v[102:105], v[140:143], v[210:213], v[102:105]
	v_mfma_f32_16x16x32_bf16 v[70:73], v[148:151], v[210:213], v[70:73]
	v_mfma_f32_16x16x32_bf16 v[98:101], v[140:143], v[218:221], v[98:101]
	v_mfma_f32_16x16x32_bf16 v[66:69], v[148:151], v[218:221], v[66:69]
	v_mfma_f32_16x16x32_bf16 v[46:49], v[152:155], v[168:171], v[46:49]
	v_mfma_f32_16x16x32_bf16 v[14:17], v[160:163], v[168:171], v[14:17]
	v_mfma_f32_16x16x32_bf16 v[42:45], v[152:155], v[182:185], v[42:45]
	v_mfma_f32_16x16x32_bf16 v[10:13], v[160:163], v[182:185], v[10:13]
	v_mfma_f32_16x16x32_bf16 v[34:37], v[152:155], v[190:193], v[34:37]
	v_mfma_f32_16x16x32_bf16 v[6:9], v[160:163], v[190:193], v[6:9]
	v_mfma_f32_16x16x32_bf16 v[26:29], v[152:155], v[214:217], v[26:29]
	v_mfma_f32_16x16x32_bf16 v[2:5], v[160:163], v[214:217], v[2:5]
	v_mfma_f32_16x16x32_bf16 v[46:49], v[156:159], v[178:181], v[46:49]
	v_mfma_f32_16x16x32_bf16 v[14:17], v[164:167], v[178:181], v[14:17]
	v_mfma_f32_16x16x32_bf16 v[42:45], v[156:159], v[186:189], v[42:45]
	v_mfma_f32_16x16x32_bf16 v[10:13], v[164:167], v[186:189], v[10:13]
	v_mfma_f32_16x16x32_bf16 v[34:37], v[156:159], v[210:213], v[34:37]
	v_mfma_f32_16x16x32_bf16 v[6:9], v[164:167], v[210:213], v[6:9]
	v_mfma_f32_16x16x32_bf16 v[26:29], v[156:159], v[218:221], v[26:29]
	v_mfma_f32_16x16x32_bf16 v[2:5], v[164:167], v[218:221], v[2:5]
	s_barrier
	s_add_u32 s25, s25, 0x80000
	s_addc_u32 s27, s27, 0
	s_add_u32 s30, s30, 0x240000
	s_addc_u32 s31, s31, 0
	s_cmp_ge_u32 s90, s17
	s_cbranch_scc1 .LBB0_116

; #define PG8_STAGE(bufoff, gbase, voff) do { _Pragma("unroll") for (int _i = 0; _i < 2; ++_i) \
;         __builtin_amdgcn_global_load_lds((const unsigned*)((const char*)(gbase) + (voff)[_i]), (LAS unsigned*)(lds + (bufoff) + ldsw + _i * 8192), 16, 0, 0); } while (0)
; #define PG8_LDA(dst, b, h) do { _Pragma("unroll") for (int m = 0; m < 4; ++m) _Pragma("unroll") for (int k = 0; k < 2; ++k) dst[m][k] = *(const LAS bf16x8*)(lds + PG8_SA(b, h) + aoff + m * 2048 + k * 1024); } while (0)
; #define PG8_LDB(dst, b, h) do { _Pragma("unroll") for (int n = 0; n < 2; ++n) _Pragma("unroll") for (int k = 0; k < 2; ++k) dst[n][k] = *(const LAS bf16x8*)(lds + PG8_SB(b, h) + boff + n * 2048 + k * 1024); } while (0)
; #define PG8_MMA(ai, bj, At, Bt) do { __builtin_amdgcn_s_setprio(1); _Pragma("unroll") for (int m = 0; m < 4; ++m) _Pragma("unroll") for (int n = 0; n < 2; ++n) _Pragma("unroll") for (int k = 0; k < 2; ++k) \
;         acc[ai][bj][m][n] = __builtin_amdgcn_mfma_f32_16x16x32_bf16(Bt[n][k], At[m][k], acc[ai][bj][m][n], 0, 0, 0); __builtin_amdgcn_s_setprio(0); } while (0)
; #define PG8_WAIT_V(n) asm volatile("s_waitcnt vmcnt(" #n ")" ::: "memory")
; #define PG8_WAIT_L(n) asm volatile("s_waitcnt lgkmcnt(" #n ")" ::: "memory")
; #define PG8_BAR __builtin_amdgcn_s_barrier()
; #define PG8_SCHED __builtin_amdgcn_sched_barrier(0)
; template <class Epi, bool ALIGN_EPI>
; __device__ __forceinline__ void gemm_phase(LAS unsigned char* lds, const int tid, const Gemm g, const StaticOrder& S, const Epi& E) {
;     ...
;             const bool last = (t == nt - 2);
;             const char* a1 = cA + (size_t)(t + 1) * kstepA;
;             const char* a2 = last ? nA : cA + (size_t)(t + 2) * kstepA; const char* b2 = last ? nB : cB + (size_t)(t + 2) * kstepB;
;             const char* a3 = a2 + kstepA; const char* b3 = b2 + kstepB;
;             PG8_LDB(B0, 0, 0); PG8_LDB(B1, 0, 1); PG8_SCHED; PG8_LDA(At, 0, 0); PG8_STAGE(PG8_SA(1, 1), a1 + hstepA, voffA);
;             PG8_WAIT_V(8); PG8_WAIT_L(0); PG8_BAR; PG8_MMA(0, 0, At, B0); PG8_MMA(0, 1, At, B1); PG8_BAR; PG8_SCHED;
;             PG8_LDA(At, 0, 1); PG8_STAGE(PG8_SB(0, 0), b2, voffB); PG8_STAGE(PG8_SB(0, 1), b2 + hstepB, voffB); PG8_STAGE(PG8_SA(0, 0), a2, voffA);
;             PG8_WAIT_V(8); PG8_WAIT_L(0); PG8_BAR; PG8_MMA(1, 0, At, B0); PG8_MMA(1, 1, At, B1); PG8_BAR; PG8_SCHED;
.LBB0_143:
	s_add_u32 s26, s24, 0xfff80080
	s_addc_u32 s27, s25, -1
	s_add_i32 s68, 0, 0x10000
	s_cmp_eq_u32 s67, 28
	s_cselect_b32 s29, s19, s27
	s_cselect_b32 s28, s18, s26
	v_add_u32_e32 v142, s68, v145
	s_cselect_b32 s27, s21, s17
	s_cselect_b32 s26, s20, s15
	s_add_i32 s70, 0, 0x14000
	ds_read_b128 v[148:151], v142
	ds_read_b128 v[152:155], v142 offset:1024
	ds_read_b128 v[156:159], v142 offset:2048
	ds_read_b128 v[160:163], v142 offset:3072
	v_add_u32_e32 v142, s70, v145
	ds_read_b128 v[164:167], v142
	ds_read_b128 v[168:171], v142 offset:1024
	ds_read_b128 v[172:175], v142 offset:2048
	ds_read_b128 v[176:179], v142 offset:3072
	s_add_i32 m0, s23, 0xc000
	ds_read_b128 v[180:183], v146
	ds_read_b128 v[184:187], v146 offset:1024
	ds_read_b128 v[188:191], v146 offset:2048
	ds_read_b128 v[192:195], v146 offset:3072
	ds_read_b128 v[210:213], v146 offset:4096
	ds_read_b128 v[214:217], v146 offset:5120
	ds_read_b128 v[218:221], v146 offset:6144
	ds_read_b128 v[222:225], v146 offset:7168
	global_load_lds_dwordx4 v140, s[24:25]
	s_add_i32 m0, s23, 0xe000
	s_nop 0
	global_load_lds_dwordx4 v138, s[24:25]
	s_sub_u32 s98, s24, 0x80000
	s_subb_u32 s99, s25, 0
	s_mov_b32 m0, s56
	s_nop 0
	global_load_lds_dwordx4 v140, s[98:99]
	s_mov_b32 m0, s58
	s_nop 0
	global_load_lds_dwordx4 v138, s[98:99]
	s_waitcnt vmcnt(8)
	s_waitcnt lgkmcnt(0)
	s_barrier
	s_waitcnt lgkmcnt(0)
	v_mfma_f32_16x16x32_bf16 v[126:129], v[148:151], v[180:183], v[126:129]
	v_mfma_f32_16x16x32_bf16 v[122:125], v[156:159], v[180:183], v[122:125]
	v_mfma_f32_16x16x32_bf16 v[110:113], v[148:151], v[188:191], v[110:113]
	v_mfma_f32_16x16x32_bf16 v[106:109], v[156:159], v[188:191], v[106:109]
	v_mfma_f32_16x16x32_bf16 v[94:97], v[148:151], v[210:213], v[94:97]
	v_mfma_f32_16x16x32_bf16 v[90:93], v[156:159], v[210:213], v[90:93]
	v_mfma_f32_16x16x32_bf16 v[78:81], v[148:151], v[218:221], v[78:81]
	v_mfma_f32_16x16x32_bf16 v[74:77], v[156:159], v[218:221], v[74:77]
	v_mfma_f32_16x16x32_bf16 v[126:129], v[152:155], v[184:187], v[126:129]
	v_mfma_f32_16x16x32_bf16 v[122:125], v[160:163], v[184:187], v[122:125]
	v_mfma_f32_16x16x32_bf16 v[110:113], v[152:155], v[192:195], v[110:113]
	v_mfma_f32_16x16x32_bf16 v[106:109], v[160:163], v[192:195], v[106:109]
	v_mfma_f32_16x16x32_bf16 v[94:97], v[152:155], v[214:217], v[94:97]
	v_mfma_f32_16x16x32_bf16 v[90:93], v[160:163], v[214:217], v[90:93]
	v_mfma_f32_16x16x32_bf16 v[78:81], v[152:155], v[222:225], v[78:81]
	v_mfma_f32_16x16x32_bf16 v[74:77], v[160:163], v[222:225], v[74:77]
	v_mfma_f32_16x16x32_bf16 v[118:121], v[164:167], v[180:183], v[118:121]
	v_mfma_f32_16x16x32_bf16 v[114:117], v[172:175], v[180:183], v[114:117]
	v_mfma_f32_16x16x32_bf16 v[102:105], v[164:167], v[188:191], v[102:105]
	v_mfma_f32_16x16x32_bf16 v[98:101], v[172:175], v[188:191], v[98:101]
	v_mfma_f32_16x16x32_bf16 v[86:89], v[164:167], v[210:213], v[86:89]
	v_mfma_f32_16x16x32_bf16 v[82:85], v[172:175], v[210:213], v[82:85]
	v_mfma_f32_16x16x32_bf16 v[70:73], v[164:167], v[218:221], v[70:73]
	v_mfma_f32_16x16x32_bf16 v[66:69], v[172:175], v[218:221], v[66:69]
	v_mfma_f32_16x16x32_bf16 v[118:121], v[168:171], v[184:187], v[118:121]
	v_mfma_f32_16x16x32_bf16 v[114:117], v[176:179], v[184:187], v[114:117]
	v_mfma_f32_16x16x32_bf16 v[102:105], v[168:171], v[192:195], v[102:105]
	v_mfma_f32_16x16x32_bf16 v[98:101], v[176:179], v[192:195], v[98:101]
	v_mfma_f32_16x16x32_bf16 v[86:89], v[168:171], v[214:217], v[86:89]
	v_mfma_f32_16x16x32_bf16 v[82:85], v[176:179], v[214:217], v[82:85]
	v_mfma_f32_16x16x32_bf16 v[70:73], v[168:171], v[222:225], v[70:73]
	v_mfma_f32_16x16x32_bf16 v[66:69], v[176:179], v[222:225], v[66:69]
	s_barrier
	s_add_i32 s68, s68, s30
	v_lshl_add_u64 v[142:143], s[26:27], 0, v[0:1]
	s_mov_b32 m0, s68
	ds_read_b128 v[180:183], v146 offset:16384
	ds_read_b128 v[184:187], v146 offset:17408
	ds_read_b128 v[188:191], v146 offset:18432
	ds_read_b128 v[192:195], v146 offset:19456
	ds_read_b128 v[210:213], v146 offset:20480
	ds_read_b128 v[214:217], v146 offset:21504
	ds_read_b128 v[218:221], v146 offset:22528
	ds_read_b128 v[222:225], v146 offset:23552
	global_load_lds_dwordx4 v0, s[26:27]
	s_add_i32 m0, s68, 0x2000
	s_add_u32 s68, s26, 0x80000
	v_lshl_add_u64 v[240:241], s[26:27], 0, v[130:131]
	s_addc_u32 s69, s27, 0
	s_add_i32 s70, s70, s30
	global_load_lds_dwordx4 v130, s[26:27]
	s_mov_b32 m0, s70
	global_load_lds_dwordx4 v0, s[68:69]
	s_add_i32 m0, s70, 0x2000
	s_nop 0
	global_load_lds_dwordx4 v130, s[68:69]
	s_waitcnt vmcnt(4)
	s_waitcnt lgkmcnt(0)
	s_barrier
	s_waitcnt lgkmcnt(0)
	v_mfma_f32_16x16x32_bf16 v[62:65], v[148:151], v[180:183], v[62:65]
	v_mfma_f32_16x16x32_bf16 v[58:61], v[156:159], v[180:183], v[58:61]
	v_mfma_f32_16x16x32_bf16 v[46:49], v[148:151], v[188:191], v[46:49]
	v_mfma_f32_16x16x32_bf16 v[42:45], v[156:159], v[188:191], v[42:45]
	v_mfma_f32_16x16x32_bf16 v[30:33], v[148:151], v[210:213], v[30:33]
	v_mfma_f32_16x16x32_bf16 v[26:29], v[156:159], v[210:213], v[26:29]
	v_mfma_f32_16x16x32_bf16 v[14:17], v[148:151], v[218:221], v[14:17]
	v_mfma_f32_16x16x32_bf16 v[10:13], v[156:159], v[218:221], v[10:13]
	v_mfma_f32_16x16x32_bf16 v[62:65], v[152:155], v[184:187], v[62:65]
	v_mfma_f32_16x16x32_bf16 v[58:61], v[160:163], v[184:187], v[58:61]
	v_mfma_f32_16x16x32_bf16 v[46:49], v[152:155], v[192:195], v[46:49]
	v_mfma_f32_16x16x32_bf16 v[42:45], v[160:163], v[192:195], v[42:45]
	v_mfma_f32_16x16x32_bf16 v[30:33], v[152:155], v[214:217], v[30:33]
	v_mfma_f32_16x16x32_bf16 v[26:29], v[160:163], v[214:217], v[26:29]
	v_mfma_f32_16x16x32_bf16 v[14:17], v[152:155], v[222:225], v[14:17]
	v_mfma_f32_16x16x32_bf16 v[10:13], v[160:163], v[222:225], v[10:13]
	v_mfma_f32_16x16x32_bf16 v[54:57], v[164:167], v[180:183], v[54:57]
	v_mfma_f32_16x16x32_bf16 v[50:53], v[172:175], v[180:183], v[50:53]
	v_mfma_f32_16x16x32_bf16 v[38:41], v[164:167], v[188:191], v[38:41]
	v_mfma_f32_16x16x32_bf16 v[34:37], v[172:175], v[188:191], v[34:37]
	v_mfma_f32_16x16x32_bf16 v[22:25], v[164:167], v[210:213], v[22:25]
	v_mfma_f32_16x16x32_bf16 v[18:21], v[172:175], v[210:213], v[18:21]
	v_mfma_f32_16x16x32_bf16 v[6:9], v[164:167], v[218:221], v[6:9]
	v_mfma_f32_16x16x32_bf16 v[2:5], v[172:175], v[218:221], v[2:5]
	v_mfma_f32_16x16x32_bf16 v[54:57], v[168:171], v[184:187], v[54:57]
	v_mfma_f32_16x16x32_bf16 v[50:53], v[176:179], v[184:187], v[50:53]
	v_mfma_f32_16x16x32_bf16 v[38:41], v[168:171], v[192:195], v[38:41]
	v_mfma_f32_16x16x32_bf16 v[34:37], v[176:179], v[192:195], v[34:37]
	v_mfma_f32_16x16x32_bf16 v[22:25], v[168:171], v[214:217], v[22:25]
	v_mfma_f32_16x16x32_bf16 v[18:21], v[176:179], v[214:217], v[18:21]
	v_mfma_f32_16x16x32_bf16 v[6:9], v[168:171], v[222:225], v[6:9]
	v_mfma_f32_16x16x32_bf16 v[2:5], v[176:179], v[222:225], v[2:5]
	s_barrier
; #define PG8_STAGE(bufoff, gbase, voff) do { _Pragma("unroll") for (int _i = 0; _i < 2; ++_i) \
;         __builtin_amdgcn_global_load_lds((const unsigned*)((const char*)(gbase) + (voff)[_i]), (LAS unsigned*)(lds + (bufoff) + ldsw + _i * 8192), 16, 0, 0); } while (0)
; #define PG8_LDA(dst, b, h) do { _Pragma("unroll") for (int m = 0; m < 4; ++m) _Pragma("unroll") for (int k = 0; k < 2; ++k) dst[m][k] = *(const LAS bf16x8*)(lds + PG8_SA(b, h) + aoff + m * 2048 + k * 1024); } while (0)
; #define PG8_LDB(dst, b, h) do { _Pragma("unroll") for (int n = 0; n < 2; ++n) _Pragma("unroll") for (int k = 0; k < 2; ++k) dst[n][k] = *(const LAS bf16x8*)(lds + PG8_SB(b, h) + boff + n * 2048 + k * 1024); } while (0)
; #define PG8_MMA(ai, bj, At, Bt) do { __builtin_amdgcn_s_setprio(1); _Pragma("unroll") for (int m = 0; m < 4; ++m) _Pragma("unroll") for (int n = 0; n < 2; ++n) _Pragma("unroll") for (int k = 0; k < 2; ++k) \
;         acc[ai][bj][m][n] = __builtin_amdgcn_mfma_f32_16x16x32_bf16(Bt[n][k], At[m][k], acc[ai][bj][m][n], 0, 0, 0); __builtin_amdgcn_s_setprio(0); } while (0)
; #define PG8_WAIT_V(n) asm volatile("s_waitcnt vmcnt(" #n ")" ::: "memory")
; #define PG8_WAIT_L(n) asm volatile("s_waitcnt lgkmcnt(" #n ")" ::: "memory")
; #define PG8_BAR __builtin_amdgcn_s_barrier()
; template <class Epi, bool ALIGN_EPI>
; __device__ __forceinline__ void gemm_phase(LAS unsigned char* lds, const int tid, const Gemm g, const StaticOrder& S, const Epi& E) {
;     ...
;             PG8_WAIT_V(8); PG8_WAIT_L(0); PG8_BAR; PG8_MMA(0, 0, At, B0); PG8_MMA(0, 1, At, B1); PG8_BAR; PG8_SCHED;
;             PG8_LDA(At, 0, 1); PG8_STAGE(PG8_SB(0, 0), b2, voffB); PG8_STAGE(PG8_SB(0, 1), b2 + hstepB, voffB); PG8_STAGE(PG8_SA(0, 0), a2, voffA);
;             PG8_WAIT_V(8); PG8_WAIT_L(0); PG8_BAR; PG8_MMA(1, 0, At, B0); PG8_MMA(1, 1, At, B1); PG8_BAR; PG8_SCHED;
;             PG8_LDB(B0, 1, 0); PG8_LDB(B1, 1, 1); PG8_SCHED; PG8_LDA(At, 1, 0); PG8_STAGE(PG8_SA(0, 1), a2 + hstepA, voffA);
;             PG8_WAIT_V(8); PG8_WAIT_L(0); PG8_BAR; PG8_MMA(0, 0, At, B0); PG8_MMA(0, 1, At, B1); PG8_BAR; PG8_SCHED;
;             PG8_LDA(At, 1, 1); PG8_STAGE(PG8_SB(1, 0), b3, voffB); PG8_STAGE(PG8_SB(1, 1), b3 + hstepB, voffB); PG8_STAGE(PG8_SA(1, 0), a3, voffA);
;             PG8_WAIT_V(8); PG8_WAIT_L(0); PG8_BAR; PG8_MMA(1, 0, At, B0); PG8_MMA(1, 1, At, B1); PG8_BAR; PG8_SCHED;
;         }
	s_add_i32 s68, 0, 0x18000
	v_add_u32_e32 v147, s68, v145
	s_add_i32 s69, 0, 0x1c000
	ds_read_b128 v[148:151], v147
	ds_read_b128 v[152:155], v147 offset:1024
	ds_read_b128 v[156:159], v147 offset:2048
	ds_read_b128 v[160:163], v147 offset:3072
	v_add_u32_e32 v147, s69, v145
	ds_read_b128 v[164:167], v147
	ds_read_b128 v[168:171], v147 offset:1024
	ds_read_b128 v[172:175], v147 offset:2048
	ds_read_b128 v[176:179], v147 offset:3072
	s_mov_b32 m0, s23
	s_nop 0
	global_load_lds_dwordx4 v134, s[28:29]
	s_mov_b32 m0, s52
	s_nop 0
	global_load_lds_dwordx4 v132, s[28:29]
	s_add_u32 s28, s28, 0x80000
	s_addc_u32 s29, s29, 0
	s_mov_b32 m0, s54
	ds_read_b128 v[180:183], v146 offset:32768
	ds_read_b128 v[184:187], v146 offset:33792
	ds_read_b128 v[188:191], v146 offset:34816
	ds_read_b128 v[192:195], v146 offset:35840
	ds_read_b128 v[210:213], v146 offset:36864
	ds_read_b128 v[214:217], v146 offset:37888
	ds_read_b128 v[218:221], v146 offset:38912
	ds_read_b128 v[222:225], v146 offset:39936
	global_load_lds_dwordx4 v134, s[28:29]
	s_mov_b32 m0, s55
	s_nop 0
	global_load_lds_dwordx4 v132, s[28:29]
	s_waitcnt vmcnt(8)
	s_waitcnt lgkmcnt(0)
	s_barrier
	s_waitcnt lgkmcnt(0)
	v_mfma_f32_16x16x32_bf16 v[126:129], v[148:151], v[180:183], v[126:129]
	v_mfma_f32_16x16x32_bf16 v[122:125], v[156:159], v[180:183], v[122:125]
	v_mfma_f32_16x16x32_bf16 v[110:113], v[148:151], v[188:191], v[110:113]
	v_mfma_f32_16x16x32_bf16 v[106:109], v[156:159], v[188:191], v[106:109]
	v_mfma_f32_16x16x32_bf16 v[94:97], v[148:151], v[210:213], v[94:97]
	v_mfma_f32_16x16x32_bf16 v[90:93], v[156:159], v[210:213], v[90:93]
	v_mfma_f32_16x16x32_bf16 v[78:81], v[148:151], v[218:221], v[78:81]
	v_mfma_f32_16x16x32_bf16 v[74:77], v[156:159], v[218:221], v[74:77]
	v_mfma_f32_16x16x32_bf16 v[126:129], v[152:155], v[184:187], v[126:129]
	v_mfma_f32_16x16x32_bf16 v[122:125], v[160:163], v[184:187], v[122:125]
	v_mfma_f32_16x16x32_bf16 v[110:113], v[152:155], v[192:195], v[110:113]
	v_mfma_f32_16x16x32_bf16 v[106:109], v[160:163], v[192:195], v[106:109]
	v_mfma_f32_16x16x32_bf16 v[94:97], v[152:155], v[214:217], v[94:97]
	v_mfma_f32_16x16x32_bf16 v[90:93], v[160:163], v[214:217], v[90:93]
	v_mfma_f32_16x16x32_bf16 v[78:81], v[152:155], v[222:225], v[78:81]
	v_mfma_f32_16x16x32_bf16 v[74:77], v[160:163], v[222:225], v[74:77]
	v_mfma_f32_16x16x32_bf16 v[118:121], v[164:167], v[180:183], v[118:121]
	v_mfma_f32_16x16x32_bf16 v[114:117], v[172:175], v[180:183], v[114:117]
	v_mfma_f32_16x16x32_bf16 v[102:105], v[164:167], v[188:191], v[102:105]
	v_mfma_f32_16x16x32_bf16 v[98:101], v[172:175], v[188:191], v[98:101]
	v_mfma_f32_16x16x32_bf16 v[86:89], v[164:167], v[210:213], v[86:89]
	v_mfma_f32_16x16x32_bf16 v[82:85], v[172:175], v[210:213], v[82:85]
	v_mfma_f32_16x16x32_bf16 v[70:73], v[164:167], v[218:221], v[70:73]
	v_mfma_f32_16x16x32_bf16 v[66:69], v[172:175], v[218:221], v[66:69]
	v_mfma_f32_16x16x32_bf16 v[118:121], v[168:171], v[184:187], v[118:121]
	v_mfma_f32_16x16x32_bf16 v[114:117], v[176:179], v[184:187], v[114:117]
	v_mfma_f32_16x16x32_bf16 v[102:105], v[168:171], v[192:195], v[102:105]
	v_mfma_f32_16x16x32_bf16 v[98:101], v[176:179], v[192:195], v[98:101]
	v_mfma_f32_16x16x32_bf16 v[86:89], v[168:171], v[214:217], v[86:89]
	v_mfma_f32_16x16x32_bf16 v[82:85], v[176:179], v[214:217], v[82:85]
	v_mfma_f32_16x16x32_bf16 v[70:73], v[168:171], v[222:225], v[70:73]
	v_mfma_f32_16x16x32_bf16 v[66:69], v[176:179], v[222:225], v[66:69]
	s_barrier
	s_add_i32 s28, s68, s30
	v_lshl_add_u64 v[142:143], v[142:143], 0, s[42:43]
	s_mov_b32 m0, s28
	ds_read_b128 v[180:183], v146 offset:49152
	ds_read_b128 v[184:187], v146 offset:50176
	ds_read_b128 v[188:191], v146 offset:51200
	ds_read_b128 v[192:195], v146 offset:52224
	ds_read_b128 v[210:213], v146 offset:53248
	ds_read_b128 v[214:217], v146 offset:54272
	ds_read_b128 v[218:221], v146 offset:55296
	ds_read_b128 v[222:225], v146 offset:56320
	global_load_lds_dwordx4 v[142:143], off
	s_add_i32 m0, s28, 0x2000
	s_add_u32 s26, s26, 0x80080
	v_lshl_add_u64 v[142:143], v[240:241], 0, s[42:43]
	s_addc_u32 s27, s27, 0
	s_add_i32 s28, s69, s30
	global_load_lds_dwordx4 v[142:143], off
	s_mov_b32 m0, s28
	s_nop 0
	global_load_lds_dwordx4 v0, s[26:27]
	v_lshl_add_u64 v[142:143], s[26:27], 0, v[130:131]
	s_add_i32 m0, s28, 0x2000
	s_nop 0
	global_load_lds_dwordx4 v130, s[26:27]
	s_waitcnt vmcnt(4)
	s_waitcnt lgkmcnt(0)
	s_barrier
	s_waitcnt lgkmcnt(0)
	v_mfma_f32_16x16x32_bf16 v[62:65], v[148:151], v[180:183], v[62:65]
	v_mfma_f32_16x16x32_bf16 v[58:61], v[156:159], v[180:183], v[58:61]
	v_mfma_f32_16x16x32_bf16 v[46:49], v[148:151], v[188:191], v[46:49]
	v_mfma_f32_16x16x32_bf16 v[42:45], v[156:159], v[188:191], v[42:45]
	v_mfma_f32_16x16x32_bf16 v[30:33], v[148:151], v[210:213], v[30:33]
	v_mfma_f32_16x16x32_bf16 v[26:29], v[156:159], v[210:213], v[26:29]
	v_mfma_f32_16x16x32_bf16 v[14:17], v[148:151], v[218:221], v[14:17]
	v_mfma_f32_16x16x32_bf16 v[10:13], v[156:159], v[218:221], v[10:13]
	v_mfma_f32_16x16x32_bf16 v[62:65], v[152:155], v[184:187], v[62:65]
	v_mfma_f32_16x16x32_bf16 v[58:61], v[160:163], v[184:187], v[58:61]
	v_mfma_f32_16x16x32_bf16 v[46:49], v[152:155], v[192:195], v[46:49]
	v_mfma_f32_16x16x32_bf16 v[42:45], v[160:163], v[192:195], v[42:45]
	v_mfma_f32_16x16x32_bf16 v[30:33], v[152:155], v[214:217], v[30:33]
	v_mfma_f32_16x16x32_bf16 v[26:29], v[160:163], v[214:217], v[26:29]
	v_mfma_f32_16x16x32_bf16 v[14:17], v[152:155], v[222:225], v[14:17]
	v_mfma_f32_16x16x32_bf16 v[10:13], v[160:163], v[222:225], v[10:13]
	v_mfma_f32_16x16x32_bf16 v[54:57], v[164:167], v[180:183], v[54:57]
	v_mfma_f32_16x16x32_bf16 v[50:53], v[172:175], v[180:183], v[50:53]
	v_mfma_f32_16x16x32_bf16 v[38:41], v[164:167], v[188:191], v[38:41]
	v_mfma_f32_16x16x32_bf16 v[34:37], v[172:175], v[188:191], v[34:37]
	v_mfma_f32_16x16x32_bf16 v[22:25], v[164:167], v[210:213], v[22:25]
	v_mfma_f32_16x16x32_bf16 v[18:21], v[172:175], v[210:213], v[18:21]
	v_mfma_f32_16x16x32_bf16 v[6:9], v[164:167], v[218:221], v[6:9]
	v_mfma_f32_16x16x32_bf16 v[2:5], v[172:175], v[218:221], v[2:5]
	v_mfma_f32_16x16x32_bf16 v[54:57], v[168:171], v[184:187], v[54:57]
	v_mfma_f32_16x16x32_bf16 v[50:53], v[176:179], v[184:187], v[50:53]
	v_mfma_f32_16x16x32_bf16 v[38:41], v[168:171], v[192:195], v[38:41]
	v_mfma_f32_16x16x32_bf16 v[34:37], v[176:179], v[192:195], v[34:37]
	v_mfma_f32_16x16x32_bf16 v[22:25], v[168:171], v[214:217], v[22:25]
	v_mfma_f32_16x16x32_bf16 v[18:21], v[176:179], v[214:217], v[18:21]
	v_mfma_f32_16x16x32_bf16 v[6:9], v[168:171], v[222:225], v[6:9]
	v_mfma_f32_16x16x32_bf16 v[2:5], v[176:179], v[222:225], v[2:5]
	s_barrier
	s_add_i32 s67, s67, 2
	s_add_u32 s15, s15, 0x100
	s_addc_u32 s17, s17, 0
	s_add_u32 s24, s24, 0x100
	s_addc_u32 s25, s25, 0
	s_cmp_gt_u32 s67, 29
	s_cbranch_scc0 .LBB0_143
	s_and_b64 vcc, exec, s[12:13]
	s_cbranch_vccz .LBB0_146
	s_barrier

; #define PG8_STAGE(bufoff, gbase, voff) do { _Pragma("unroll") for (int _i = 0; _i < 2; ++_i) \
;         __builtin_amdgcn_global_load_lds((const unsigned*)((const char*)(gbase) + (voff)[_i]), (LAS unsigned*)(lds + (bufoff) + ldsw + _i * 8192), 16, 0, 0); } while (0)
; #define PG8_LDA(dst, b, h) do { _Pragma("unroll") for (int m = 0; m < 4; ++m) _Pragma("unroll") for (int k = 0; k < 2; ++k) dst[m][k] = *(const LAS bf16x8*)(lds + PG8_SA(b, h) + aoff + m * 2048 + k * 1024); } while (0)
; #define PG8_LDB(dst, b, h) do { _Pragma("unroll") for (int n = 0; n < 2; ++n) _Pragma("unroll") for (int k = 0; k < 2; ++k) dst[n][k] = *(const LAS bf16x8*)(lds + PG8_SB(b, h) + boff + n * 2048 + k * 1024); } while (0)
; #define PG8_MMA(ai, bj, At, Bt) do { __builtin_amdgcn_s_setprio(1); _Pragma("unroll") for (int m = 0; m < 4; ++m) _Pragma("unroll") for (int n = 0; n < 2; ++n) _Pragma("unroll") for (int k = 0; k < 2; ++k) \
;         acc[ai][bj][m][n] = __builtin_amdgcn_mfma_f32_16x16x32_bf16(Bt[n][k], At[m][k], acc[ai][bj][m][n], 0, 0, 0); __builtin_amdgcn_s_setprio(0); } while (0)
; #define PG8_WAIT_V(n) asm volatile("s_waitcnt vmcnt(" #n ")" ::: "memory")
; #define PG8_WAIT_L(n) asm volatile("s_waitcnt lgkmcnt(" #n ")" ::: "memory")
; #define PG8_BAR __builtin_amdgcn_s_barrier()
; #define PG8_SCHED __builtin_amdgcn_sched_barrier(0)
; template <class Epi, bool ALIGN_EPI>
; __device__ __forceinline__ void gemm_phase(LAS unsigned char* lds, const int tid, const Gemm g, const StaticOrder& S, const Epi& E) {
;     ...
;             const bool last = (t == nt - 2);
;             const char* a1 = cA + (size_t)(t + 1) * kstepA;
;             const char* a2 = last ? nA : cA + (size_t)(t + 2) * kstepA; const char* b2 = last ? nB : cB + (size_t)(t + 2) * kstepB;
;             const char* a3 = a2 + kstepA; const char* b3 = b2 + kstepB;
;             PG8_LDB(B0, 0, 0); PG8_LDB(B1, 0, 1); PG8_SCHED; PG8_LDA(At, 0, 0); PG8_STAGE(PG8_SA(1, 1), a1 + hstepA, voffA);
;             PG8_WAIT_V(8); PG8_WAIT_L(0); PG8_BAR; PG8_MMA(0, 0, At, B0); PG8_MMA(0, 1, At, B1); PG8_BAR; PG8_SCHED;
;             PG8_LDA(At, 0, 1); PG8_STAGE(PG8_SB(0, 0), b2, voffB); PG8_STAGE(PG8_SB(0, 1), b2 + hstepB, voffB); PG8_STAGE(PG8_SA(0, 0), a2, voffA);
;             PG8_WAIT_V(8); PG8_WAIT_L(0); PG8_BAR; PG8_MMA(1, 0, At, B0); PG8_MMA(1, 1, At, B1); PG8_BAR; PG8_SCHED;
.LBB0_209:
	s_add_i32 s72, s34, 2
	s_add_u32 s35, s30, 0xfff80080
	s_addc_u32 s54, s31, -1
	s_cmp_eq_u32 s21, s34
	s_cselect_b32 s55, s23, s54
	s_cselect_b32 s54, s22, s35
	s_cselect_b32 s35, s25, s71
	s_cselect_b32 s34, s24, s27
	s_add_i32 s73, 0, 0x10000
	s_add_i32 s85, 0, 0x14000
	v_add_u32_e32 v148, s73, v175
	v_add_u32_e32 v164, s85, v175
	ds_read_b128 v[136:139], v148
	ds_read_b128 v[140:143], v148 offset:1024
	ds_read_b128 v[144:147], v148 offset:2048
	ds_read_b128 v[148:151], v148 offset:3072
	ds_read_b128 v[152:155], v164
	ds_read_b128 v[156:159], v164 offset:1024
	ds_read_b128 v[160:163], v164 offset:2048
	ds_read_b128 v[164:167], v164 offset:3072
	s_add_i32 m0, s58, 0xc000
	ds_read_b128 v[168:171], v177
	ds_read_b128 v[178:181], v177 offset:1024
	ds_read_b128 v[182:185], v177 offset:2048
	ds_read_b128 v[186:189], v177 offset:3072
	ds_read_b128 v[190:193], v177 offset:4096
	ds_read_b128 v[210:213], v177 offset:5120
	ds_read_b128 v[214:217], v177 offset:6144
	ds_read_b128 v[218:221], v177 offset:7168
	global_load_lds_dwordx4 v134, s[30:31]
	s_add_i32 m0, s58, 0xe000
	s_nop 0
	global_load_lds_dwordx4 v132, s[30:31]
	s_sub_u32 s98, s30, 0x80000
	s_subb_u32 s99, s31, 0
	s_mov_b32 m0, s65
	s_nop 0
	global_load_lds_dwordx4 v134, s[98:99]
	s_mov_b32 m0, s66
	s_nop 0
	global_load_lds_dwordx4 v132, s[98:99]
	s_waitcnt vmcnt(8)
	s_waitcnt lgkmcnt(0)
	s_barrier
	s_waitcnt lgkmcnt(0)
	v_mfma_f32_16x16x32_bf16 v[126:129], v[136:139], v[168:171], v[126:129]
	v_mfma_f32_16x16x32_bf16 v[94:97], v[144:147], v[168:171], v[94:97]
	v_mfma_f32_16x16x32_bf16 v[122:125], v[136:139], v[182:185], v[122:125]
	v_mfma_f32_16x16x32_bf16 v[90:93], v[144:147], v[182:185], v[90:93]
	v_mfma_f32_16x16x32_bf16 v[118:121], v[136:139], v[190:193], v[118:121]
	v_mfma_f32_16x16x32_bf16 v[86:89], v[144:147], v[190:193], v[86:89]
	v_mfma_f32_16x16x32_bf16 v[114:117], v[136:139], v[214:217], v[114:117]
	v_mfma_f32_16x16x32_bf16 v[82:85], v[144:147], v[214:217], v[82:85]
	v_mfma_f32_16x16x32_bf16 v[126:129], v[140:143], v[178:181], v[126:129]
	v_mfma_f32_16x16x32_bf16 v[94:97], v[148:151], v[178:181], v[94:97]
	v_mfma_f32_16x16x32_bf16 v[122:125], v[140:143], v[186:189], v[122:125]
	v_mfma_f32_16x16x32_bf16 v[90:93], v[148:151], v[186:189], v[90:93]
	v_mfma_f32_16x16x32_bf16 v[118:121], v[140:143], v[210:213], v[118:121]
	v_mfma_f32_16x16x32_bf16 v[86:89], v[148:151], v[210:213], v[86:89]
	v_mfma_f32_16x16x32_bf16 v[114:117], v[140:143], v[218:221], v[114:117]
	v_mfma_f32_16x16x32_bf16 v[82:85], v[148:151], v[218:221], v[82:85]
	v_mfma_f32_16x16x32_bf16 v[62:65], v[152:155], v[168:171], v[62:65]
	v_mfma_f32_16x16x32_bf16 v[42:45], v[160:163], v[168:171], v[42:45]
	v_mfma_f32_16x16x32_bf16 v[58:61], v[152:155], v[182:185], v[58:61]
	v_mfma_f32_16x16x32_bf16 v[34:37], v[160:163], v[182:185], v[34:37]
	v_mfma_f32_16x16x32_bf16 v[54:57], v[152:155], v[190:193], v[54:57]
	v_mfma_f32_16x16x32_bf16 v[26:29], v[160:163], v[190:193], v[26:29]
	v_mfma_f32_16x16x32_bf16 v[50:53], v[152:155], v[214:217], v[50:53]
	v_mfma_f32_16x16x32_bf16 v[18:21], v[160:163], v[214:217], v[18:21]
	v_mfma_f32_16x16x32_bf16 v[62:65], v[156:159], v[178:181], v[62:65]
	v_mfma_f32_16x16x32_bf16 v[42:45], v[164:167], v[178:181], v[42:45]
	v_mfma_f32_16x16x32_bf16 v[58:61], v[156:159], v[186:189], v[58:61]
	v_mfma_f32_16x16x32_bf16 v[34:37], v[164:167], v[186:189], v[34:37]
	v_mfma_f32_16x16x32_bf16 v[54:57], v[156:159], v[210:213], v[54:57]
	v_mfma_f32_16x16x32_bf16 v[26:29], v[164:167], v[210:213], v[26:29]
	v_mfma_f32_16x16x32_bf16 v[50:53], v[156:159], v[218:221], v[50:53]
	v_mfma_f32_16x16x32_bf16 v[18:21], v[164:167], v[218:221], v[18:21]
	s_barrier
	s_add_i32 s73, s73, s56
	v_lshl_add_u64 v[172:173], s[34:35], 0, v[0:1]
	s_mov_b32 m0, s73
	ds_read_b128 v[168:171], v177 offset:16384
	ds_read_b128 v[178:181], v177 offset:17408
	ds_read_b128 v[182:185], v177 offset:18432
	ds_read_b128 v[186:189], v177 offset:19456
	ds_read_b128 v[190:193], v177 offset:20480
	ds_read_b128 v[210:213], v177 offset:21504
	ds_read_b128 v[214:217], v177 offset:22528
	ds_read_b128 v[218:221], v177 offset:23552
	global_load_lds_dwordx4 v0, s[34:35]
	s_add_i32 m0, s73, 0x2000
	s_add_u32 s90, s34, 0x80000
	v_lshl_add_u64 v[194:195], s[34:35], 0, v[130:131]
	s_addc_u32 s91, s35, 0
	s_add_i32 s73, s85, s56
	global_load_lds_dwordx4 v130, s[34:35]
	s_mov_b32 m0, s73
	global_load_lds_dwordx4 v0, s[90:91]
	s_add_i32 m0, s73, 0x2000
	s_nop 0
	global_load_lds_dwordx4 v130, s[90:91]
	s_waitcnt vmcnt(4)
	s_waitcnt lgkmcnt(0)
	s_barrier
; #define PG8_STAGE(bufoff, gbase, voff) do { _Pragma("unroll") for (int _i = 0; _i < 2; ++_i) \
;         __builtin_amdgcn_global_load_lds((const unsigned*)((const char*)(gbase) + (voff)[_i]), (LAS unsigned*)(lds + (bufoff) + ldsw + _i * 8192), 16, 0, 0); } while (0)
; #define PG8_LDA(dst, b, h) do { _Pragma("unroll") for (int m = 0; m < 4; ++m) _Pragma("unroll") for (int k = 0; k < 2; ++k) dst[m][k] = *(const LAS bf16x8*)(lds + PG8_SA(b, h) + aoff + m * 2048 + k * 1024); } while (0)
; #define PG8_LDB(dst, b, h) do { _Pragma("unroll") for (int n = 0; n < 2; ++n) _Pragma("unroll") for (int k = 0; k < 2; ++k) dst[n][k] = *(const LAS bf16x8*)(lds + PG8_SB(b, h) + boff + n * 2048 + k * 1024); } while (0)
; #define PG8_MMA(ai, bj, At, Bt) do { __builtin_amdgcn_s_setprio(1); _Pragma("unroll") for (int m = 0; m < 4; ++m) _Pragma("unroll") for (int n = 0; n < 2; ++n) _Pragma("unroll") for (int k = 0; k < 2; ++k) \
;         acc[ai][bj][m][n] = __builtin_amdgcn_mfma_f32_16x16x32_bf16(Bt[n][k], At[m][k], acc[ai][bj][m][n], 0, 0, 0); __builtin_amdgcn_s_setprio(0); } while (0)
; #define PG8_WAIT_V(n) asm volatile("s_waitcnt vmcnt(" #n ")" ::: "memory")
; #define PG8_WAIT_L(n) asm volatile("s_waitcnt lgkmcnt(" #n ")" ::: "memory")
; #define PG8_BAR __builtin_amdgcn_s_barrier()
; #define PG8_SCHED __builtin_amdgcn_sched_barrier(0)
; template <class Epi, bool ALIGN_EPI>
; __device__ __forceinline__ void gemm_phase(LAS unsigned char* lds, const int tid, const Gemm g, const StaticOrder& S, const Epi& E) {
;     ...
;             PG8_WAIT_V(8); PG8_WAIT_L(0); PG8_BAR; PG8_MMA(1, 0, At, B0); PG8_MMA(1, 1, At, B1); PG8_BAR; PG8_SCHED;
;             PG8_LDB(B0, 1, 0); PG8_LDB(B1, 1, 1); PG8_SCHED; PG8_LDA(At, 1, 0); PG8_STAGE(PG8_SA(0, 1), a2 + hstepA, voffA);
;             PG8_WAIT_V(8); PG8_WAIT_L(0); PG8_BAR; PG8_MMA(0, 0, At, B0); PG8_MMA(0, 1, At, B1); PG8_BAR; PG8_SCHED;
	s_waitcnt lgkmcnt(0)
	v_mfma_f32_16x16x32_bf16 v[110:113], v[136:139], v[168:171], v[110:113]
	v_mfma_f32_16x16x32_bf16 v[78:81], v[144:147], v[168:171], v[78:81]
	v_mfma_f32_16x16x32_bf16 v[106:109], v[136:139], v[182:185], v[106:109]
	v_mfma_f32_16x16x32_bf16 v[74:77], v[144:147], v[182:185], v[74:77]
	v_mfma_f32_16x16x32_bf16 v[102:105], v[136:139], v[190:193], v[102:105]
	v_mfma_f32_16x16x32_bf16 v[70:73], v[144:147], v[190:193], v[70:73]
	v_mfma_f32_16x16x32_bf16 v[98:101], v[136:139], v[214:217], v[98:101]
	v_mfma_f32_16x16x32_bf16 v[66:69], v[144:147], v[214:217], v[66:69]
	v_mfma_f32_16x16x32_bf16 v[110:113], v[140:143], v[178:181], v[110:113]
	v_mfma_f32_16x16x32_bf16 v[78:81], v[148:151], v[178:181], v[78:81]
	v_mfma_f32_16x16x32_bf16 v[106:109], v[140:143], v[186:189], v[106:109]
	v_mfma_f32_16x16x32_bf16 v[74:77], v[148:151], v[186:189], v[74:77]
	v_mfma_f32_16x16x32_bf16 v[102:105], v[140:143], v[210:213], v[102:105]
	v_mfma_f32_16x16x32_bf16 v[70:73], v[148:151], v[210:213], v[70:73]
	v_mfma_f32_16x16x32_bf16 v[98:101], v[140:143], v[218:221], v[98:101]
	v_mfma_f32_16x16x32_bf16 v[66:69], v[148:151], v[218:221], v[66:69]
	v_mfma_f32_16x16x32_bf16 v[46:49], v[152:155], v[168:171], v[46:49]
	v_mfma_f32_16x16x32_bf16 v[14:17], v[160:163], v[168:171], v[14:17]
	v_mfma_f32_16x16x32_bf16 v[38:41], v[152:155], v[182:185], v[38:41]
	v_mfma_f32_16x16x32_bf16 v[10:13], v[160:163], v[182:185], v[10:13]
	v_mfma_f32_16x16x32_bf16 v[30:33], v[152:155], v[190:193], v[30:33]
	v_mfma_f32_16x16x32_bf16 v[6:9], v[160:163], v[190:193], v[6:9]
	v_mfma_f32_16x16x32_bf16 v[22:25], v[152:155], v[214:217], v[22:25]
	v_mfma_f32_16x16x32_bf16 v[2:5], v[160:163], v[214:217], v[2:5]
	v_mfma_f32_16x16x32_bf16 v[46:49], v[156:159], v[178:181], v[46:49]
	v_mfma_f32_16x16x32_bf16 v[14:17], v[164:167], v[178:181], v[14:17]
	v_mfma_f32_16x16x32_bf16 v[38:41], v[156:159], v[186:189], v[38:41]
	v_mfma_f32_16x16x32_bf16 v[10:13], v[164:167], v[186:189], v[10:13]
	v_mfma_f32_16x16x32_bf16 v[30:33], v[156:159], v[210:213], v[30:33]
	v_mfma_f32_16x16x32_bf16 v[6:9], v[164:167], v[210:213], v[6:9]
	v_mfma_f32_16x16x32_bf16 v[22:25], v[156:159], v[218:221], v[22:25]
	v_mfma_f32_16x16x32_bf16 v[2:5], v[164:167], v[218:221], v[2:5]
	s_barrier
	s_add_i32 s73, 0, 0x18000
	s_add_i32 s85, 0, 0x1c000
	v_add_u32_e32 v148, s73, v175
	v_add_u32_e32 v164, s85, v175
	ds_read_b128 v[136:139], v148
	ds_read_b128 v[140:143], v148 offset:1024
	ds_read_b128 v[144:147], v148 offset:2048
	ds_read_b128 v[148:151], v148 offset:3072
	ds_read_b128 v[152:155], v164
	ds_read_b128 v[156:159], v164 offset:1024
	ds_read_b128 v[160:163], v164 offset:2048
	ds_read_b128 v[164:167], v164 offset:3072
	s_mov_b32 m0, s58
	s_nop 0
	global_load_lds_dwordx4 v0, s[54:55]
	s_mov_b32 m0, s60
	s_nop 0
	global_load_lds_dwordx4 v130, s[54:55]
	s_add_u32 s54, s54, 0x80000
	s_addc_u32 s55, s55, 0
	s_mov_b32 m0, s61
	ds_read_b128 v[168:171], v177 offset:32768
	ds_read_b128 v[178:181], v177 offset:33792
	ds_read_b128 v[182:185], v177 offset:34816
	ds_read_b128 v[186:189], v177 offset:35840
	ds_read_b128 v[190:193], v177 offset:36864
	ds_read_b128 v[210:213], v177 offset:37888
	ds_read_b128 v[214:217], v177 offset:38912
	ds_read_b128 v[218:221], v177 offset:39936
	global_load_lds_dwordx4 v0, s[54:55]
	s_mov_b32 m0, s62
	s_nop 0
	global_load_lds_dwordx4 v130, s[54:55]
	s_waitcnt vmcnt(8)
	s_waitcnt lgkmcnt(0)
	s_barrier
; #define PG8_STAGE(bufoff, gbase, voff) do { _Pragma("unroll") for (int _i = 0; _i < 2; ++_i) \
;         __builtin_amdgcn_global_load_lds((const unsigned*)((const char*)(gbase) + (voff)[_i]), (LAS unsigned*)(lds + (bufoff) + ldsw + _i * 8192), 16, 0, 0); } while (0)
; #define PG8_LDA(dst, b, h) do { _Pragma("unroll") for (int m = 0; m < 4; ++m) _Pragma("unroll") for (int k = 0; k < 2; ++k) dst[m][k] = *(const LAS bf16x8*)(lds + PG8_SA(b, h) + aoff + m * 2048 + k * 1024); } while (0)
; #define PG8_MMA(ai, bj, At, Bt) do { __builtin_amdgcn_s_setprio(1); _Pragma("unroll") for (int m = 0; m < 4; ++m) _Pragma("unroll") for (int n = 0; n < 2; ++n) _Pragma("unroll") for (int k = 0; k < 2; ++k) \
;         acc[ai][bj][m][n] = __builtin_amdgcn_mfma_f32_16x16x32_bf16(Bt[n][k], At[m][k], acc[ai][bj][m][n], 0, 0, 0); __builtin_amdgcn_s_setprio(0); } while (0)
; #define PG8_WAIT_V(n) asm volatile("s_waitcnt vmcnt(" #n ")" ::: "memory")
; #define PG8_WAIT_L(n) asm volatile("s_waitcnt lgkmcnt(" #n ")" ::: "memory")
; #define PG8_BAR __builtin_amdgcn_s_barrier()
; #define PG8_SCHED __builtin_amdgcn_sched_barrier(0)
; template <class Epi, bool ALIGN_EPI>
; __device__ __forceinline__ void gemm_phase(LAS unsigned char* lds, const int tid, const Gemm g, const StaticOrder& S, const Epi& E) {
;     ...
;             PG8_WAIT_V(8); PG8_WAIT_L(0); PG8_BAR; PG8_MMA(0, 0, At, B0); PG8_MMA(0, 1, At, B1); PG8_BAR; PG8_SCHED;
;             PG8_LDA(At, 1, 1); PG8_STAGE(PG8_SB(1, 0), b3, voffB); PG8_STAGE(PG8_SB(1, 1), b3 + hstepB, voffB); PG8_STAGE(PG8_SA(1, 0), a3, voffA);
;             PG8_WAIT_V(8); PG8_WAIT_L(0); PG8_BAR; PG8_MMA(1, 0, At, B0); PG8_MMA(1, 1, At, B1); PG8_BAR; PG8_SCHED;
;         }
;         if constexpr (ALIGN_EPI) { if (wr == 0) PG8_BAR; }
	s_waitcnt lgkmcnt(0)
	v_mfma_f32_16x16x32_bf16 v[126:129], v[136:139], v[168:171], v[126:129]
	v_mfma_f32_16x16x32_bf16 v[94:97], v[144:147], v[168:171], v[94:97]
	v_mfma_f32_16x16x32_bf16 v[122:125], v[136:139], v[182:185], v[122:125]
	v_mfma_f32_16x16x32_bf16 v[90:93], v[144:147], v[182:185], v[90:93]
	v_mfma_f32_16x16x32_bf16 v[118:121], v[136:139], v[190:193], v[118:121]
	v_mfma_f32_16x16x32_bf16 v[86:89], v[144:147], v[190:193], v[86:89]
	v_mfma_f32_16x16x32_bf16 v[114:117], v[136:139], v[214:217], v[114:117]
	v_mfma_f32_16x16x32_bf16 v[82:85], v[144:147], v[214:217], v[82:85]
	v_mfma_f32_16x16x32_bf16 v[126:129], v[140:143], v[178:181], v[126:129]
	v_mfma_f32_16x16x32_bf16 v[94:97], v[148:151], v[178:181], v[94:97]
	v_mfma_f32_16x16x32_bf16 v[122:125], v[140:143], v[186:189], v[122:125]
	v_mfma_f32_16x16x32_bf16 v[90:93], v[148:151], v[186:189], v[90:93]
	v_mfma_f32_16x16x32_bf16 v[118:121], v[140:143], v[210:213], v[118:121]
	v_mfma_f32_16x16x32_bf16 v[86:89], v[148:151], v[210:213], v[86:89]
	v_mfma_f32_16x16x32_bf16 v[114:117], v[140:143], v[218:221], v[114:117]
	v_mfma_f32_16x16x32_bf16 v[82:85], v[148:151], v[218:221], v[82:85]
	v_mfma_f32_16x16x32_bf16 v[62:65], v[152:155], v[168:171], v[62:65]
	v_mfma_f32_16x16x32_bf16 v[42:45], v[160:163], v[168:171], v[42:45]
	v_mfma_f32_16x16x32_bf16 v[58:61], v[152:155], v[182:185], v[58:61]
	v_mfma_f32_16x16x32_bf16 v[34:37], v[160:163], v[182:185], v[34:37]
	v_mfma_f32_16x16x32_bf16 v[54:57], v[152:155], v[190:193], v[54:57]
	v_mfma_f32_16x16x32_bf16 v[26:29], v[160:163], v[190:193], v[26:29]
	v_mfma_f32_16x16x32_bf16 v[50:53], v[152:155], v[214:217], v[50:53]
	v_mfma_f32_16x16x32_bf16 v[18:21], v[160:163], v[214:217], v[18:21]
	v_mfma_f32_16x16x32_bf16 v[62:65], v[156:159], v[178:181], v[62:65]
	v_mfma_f32_16x16x32_bf16 v[42:45], v[164:167], v[178:181], v[42:45]
	v_mfma_f32_16x16x32_bf16 v[58:61], v[156:159], v[186:189], v[58:61]
	v_mfma_f32_16x16x32_bf16 v[34:37], v[164:167], v[186:189], v[34:37]
	v_mfma_f32_16x16x32_bf16 v[54:57], v[156:159], v[210:213], v[54:57]
	v_mfma_f32_16x16x32_bf16 v[26:29], v[164:167], v[210:213], v[26:29]
	v_mfma_f32_16x16x32_bf16 v[50:53], v[156:159], v[218:221], v[50:53]
	v_mfma_f32_16x16x32_bf16 v[18:21], v[164:167], v[218:221], v[18:21]
	s_barrier
	s_add_i32 s54, s73, s56
	v_lshl_add_u64 v[172:173], v[172:173], 0, s[42:43]
	s_mov_b32 m0, s54
	ds_read_b128 v[168:171], v177 offset:49152
	ds_read_b128 v[178:181], v177 offset:50176
	ds_read_b128 v[182:185], v177 offset:51200
	ds_read_b128 v[186:189], v177 offset:52224
	ds_read_b128 v[190:193], v177 offset:53248
	ds_read_b128 v[210:213], v177 offset:54272
	ds_read_b128 v[214:217], v177 offset:55296
	ds_read_b128 v[218:221], v177 offset:56320
	global_load_lds_dwordx4 v[172:173], off
	s_add_i32 m0, s54, 0x2000
	s_add_u32 s34, s34, 0x80080
	v_lshl_add_u64 v[172:173], v[194:195], 0, s[42:43]
	s_addc_u32 s35, s35, 0
	s_add_i32 s54, s85, s56
	global_load_lds_dwordx4 v[172:173], off
	s_mov_b32 m0, s54
	s_nop 0
	global_load_lds_dwordx4 v0, s[34:35]
	s_add_i32 m0, s54, 0x2000
	s_nop 0
	global_load_lds_dwordx4 v130, s[34:35]
	s_waitcnt vmcnt(4)
	s_waitcnt lgkmcnt(0)
	s_barrier
	s_waitcnt lgkmcnt(0)
	v_mfma_f32_16x16x32_bf16 v[110:113], v[136:139], v[168:171], v[110:113]
	v_mfma_f32_16x16x32_bf16 v[78:81], v[144:147], v[168:171], v[78:81]
	v_mfma_f32_16x16x32_bf16 v[106:109], v[136:139], v[182:185], v[106:109]
	v_mfma_f32_16x16x32_bf16 v[74:77], v[144:147], v[182:185], v[74:77]
	v_mfma_f32_16x16x32_bf16 v[102:105], v[136:139], v[190:193], v[102:105]
	v_mfma_f32_16x16x32_bf16 v[70:73], v[144:147], v[190:193], v[70:73]
	v_mfma_f32_16x16x32_bf16 v[98:101], v[136:139], v[214:217], v[98:101]
	v_mfma_f32_16x16x32_bf16 v[66:69], v[144:147], v[214:217], v[66:69]
	v_mfma_f32_16x16x32_bf16 v[110:113], v[140:143], v[178:181], v[110:113]
	v_mfma_f32_16x16x32_bf16 v[78:81], v[148:151], v[178:181], v[78:81]
	v_mfma_f32_16x16x32_bf16 v[106:109], v[140:143], v[186:189], v[106:109]
	v_mfma_f32_16x16x32_bf16 v[74:77], v[148:151], v[186:189], v[74:77]
	v_mfma_f32_16x16x32_bf16 v[102:105], v[140:143], v[210:213], v[102:105]
	v_mfma_f32_16x16x32_bf16 v[70:73], v[148:151], v[210:213], v[70:73]
	v_mfma_f32_16x16x32_bf16 v[98:101], v[140:143], v[218:221], v[98:101]
	v_mfma_f32_16x16x32_bf16 v[66:69], v[148:151], v[218:221], v[66:69]
	v_mfma_f32_16x16x32_bf16 v[46:49], v[152:155], v[168:171], v[46:49]
	v_mfma_f32_16x16x32_bf16 v[14:17], v[160:163], v[168:171], v[14:17]
	v_mfma_f32_16x16x32_bf16 v[38:41], v[152:155], v[182:185], v[38:41]
	v_mfma_f32_16x16x32_bf16 v[10:13], v[160:163], v[182:185], v[10:13]
	v_mfma_f32_16x16x32_bf16 v[30:33], v[152:155], v[190:193], v[30:33]
	v_mfma_f32_16x16x32_bf16 v[6:9], v[160:163], v[190:193], v[6:9]
	v_mfma_f32_16x16x32_bf16 v[22:25], v[152:155], v[214:217], v[22:25]
	v_mfma_f32_16x16x32_bf16 v[2:5], v[160:163], v[214:217], v[2:5]
	v_mfma_f32_16x16x32_bf16 v[46:49], v[156:159], v[178:181], v[46:49]
	v_mfma_f32_16x16x32_bf16 v[14:17], v[164:167], v[178:181], v[14:17]
	v_mfma_f32_16x16x32_bf16 v[38:41], v[156:159], v[186:189], v[38:41]
	v_mfma_f32_16x16x32_bf16 v[10:13], v[164:167], v[186:189], v[10:13]
	v_mfma_f32_16x16x32_bf16 v[30:33], v[156:159], v[210:213], v[30:33]
	v_mfma_f32_16x16x32_bf16 v[6:9], v[164:167], v[210:213], v[6:9]
	v_mfma_f32_16x16x32_bf16 v[22:25], v[156:159], v[218:221], v[22:25]
	v_mfma_f32_16x16x32_bf16 v[2:5], v[164:167], v[218:221], v[2:5]
	s_barrier
	s_add_u32 s27, s27, 0x100
	s_addc_u32 s71, s71, 0
	s_add_u32 s30, s30, 0x100
	s_addc_u32 s31, s31, 0
	s_cmp_ge_u32 s72, s19
	s_mov_b32 s34, s72
	s_cbranch_scc0 .LBB0_209
	s_and_b64 vcc, exec, s[16:17]
	s_cbranch_vccz .LBB0_212
	s_barrier

; #define PG8_STAGE(bufoff, gbase, voff) do { _Pragma("unroll") for (int _i = 0; _i < 2; ++_i) \
;         __builtin_amdgcn_global_load_lds((const unsigned*)((const char*)(gbase) + (voff)[_i]), (LAS unsigned*)(lds + (bufoff) + ldsw + _i * 8192), 16, 0, 0); } while (0)
; #define PG8_LDA(dst, b, h) do { _Pragma("unroll") for (int m = 0; m < 4; ++m) _Pragma("unroll") for (int k = 0; k < 2; ++k) dst[m][k] = *(const LAS bf16x8*)(lds + PG8_SA(b, h) + aoff + m * 2048 + k * 1024); } while (0)
; #define PG8_LDB(dst, b, h) do { _Pragma("unroll") for (int n = 0; n < 2; ++n) _Pragma("unroll") for (int k = 0; k < 2; ++k) dst[n][k] = *(const LAS bf16x8*)(lds + PG8_SB(b, h) + boff + n * 2048 + k * 1024); } while (0)
; #define PG8_WAIT_V(n) asm volatile("s_waitcnt vmcnt(" #n ")" ::: "memory")
; #define PG8_WAIT_L(n) asm volatile("s_waitcnt lgkmcnt(" #n ")" ::: "memory")
; #define PG8_BAR __builtin_amdgcn_s_barrier()
; template <class Epi, bool ALIGN_EPI>
; __device__ __forceinline__ void gemm_phase(LAS unsigned char* lds, const int tid, const Gemm g, const StaticOrder& S, const Epi& E) {
;     ...
;         const bool has_next = S.next(ui + 1, nxt);
;         const char* nA = has_next ? (const char*)g.A + (size_t)nxt.pm * tstepA + PG8_KOFFA(nxt) : cA; const char* nB = has_next ? (const char*)g.Bt + (size_t)nxt.pn * tstepB + PG8_KOFFB(nxt) : cB;
;         const int nt = cur.ks >= 0 ? nt_split : nt_full;
;         for (int t = 0; t < nt; t += 2) {
;             if constexpr (Epi::HOOK) { if (t != 0 && (t & 7) == 0) E.hook(acc, cur, (t >> 3) - 1, wr, wc, fr, fq); }
;             const bool last = (t == nt - 2);
;             const char* a1 = cA + (size_t)(t + 1) * kstepA;
;             const char* a2 = last ? nA : cA + (size_t)(t + 2) * kstepA; const char* b2 = last ? nB : cB + (size_t)(t + 2) * kstepB;
;             const char* a3 = a2 + kstepA; const char* b3 = b2 + kstepB;
;             PG8_LDB(B0, 0, 0); PG8_LDB(B1, 0, 1); PG8_SCHED; PG8_LDA(At, 0, 0); PG8_STAGE(PG8_SA(1, 1), a1 + hstepA, voffA);
;             PG8_WAIT_V(8); PG8_WAIT_L(0); PG8_BAR; PG8_MMA(0, 0, At, B0); PG8_MMA(0, 1, At, B1); PG8_BAR; PG8_SCHED;
;             PG8_LDA(At, 0, 1); PG8_STAGE(PG8_SB(0, 0), b2, voffB); PG8_STAGE(PG8_SB(0, 1), b2 + hstepB, voffB); PG8_STAGE(PG8_SA(0, 0), a2, voffA);
;             PG8_WAIT_V(8); PG8_WAIT_L(0); PG8_BAR; PG8_MMA(1, 0, At, B0); PG8_MMA(1, 1, At, B1); PG8_BAR; PG8_SCHED;
.LBB0_263:
	s_add_i32 s5, s5, 2
	s_add_u32 s34, s30, 0xfff80080
	s_addc_u32 s35, s31, -1
	s_add_i32 s94, 0, 0x10000
	s_cmp_eq_u32 s91, s92
	s_cselect_b32 s55, s23, s35
	s_cselect_b32 s54, s22, s34
	v_add_u32_e32 v0, s94, v205
	s_cselect_b32 s35, s25, s36
	s_cselect_b32 s34, s24, s21
	s_add_i32 s96, 0, 0x14000
	ds_read_b128 v[132:135], v0
	ds_read_b128 v[136:139], v0 offset:1024
	ds_read_b128 v[140:143], v0 offset:2048
	ds_read_b128 v[144:147], v0 offset:3072
	v_add_u32_e32 v0, s96, v205
	ds_read_b128 v[148:151], v0
	ds_read_b128 v[152:155], v0 offset:1024
	ds_read_b128 v[156:159], v0 offset:2048
	ds_read_b128 v[160:163], v0 offset:3072
	s_add_i32 m0, s68, 0xc000
	ds_read_b128 v[164:167], v209
	ds_read_b128 v[168:171], v209 offset:1024
	ds_read_b128 v[172:175], v209 offset:2048
	ds_read_b128 v[176:179], v209 offset:3072
	ds_read_b128 v[180:183], v209 offset:4096
	ds_read_b128 v[184:187], v209 offset:5120
	ds_read_b128 v[188:191], v209 offset:6144
	ds_read_b128 v[192:195], v209 offset:7168
	global_load_lds_dwordx4 v220, s[30:31]
	s_add_i32 m0, s68, 0xe000
	s_nop 0
	global_load_lds_dwordx4 v218, s[30:31]
	s_sub_u32 s98, s30, 0x80000
	s_subb_u32 s99, s31, 0
	s_mov_b32 m0, s72
	s_nop 0
	global_load_lds_dwordx4 v220, s[98:99]
	s_mov_b32 m0, s73
	s_nop 0
	global_load_lds_dwordx4 v218, s[98:99]
	s_waitcnt vmcnt(8)
	s_waitcnt lgkmcnt(0)
	s_barrier
	s_waitcnt lgkmcnt(0)
	v_mfma_f32_16x16x32_bf16 v[128:131], v[132:135], v[164:167], v[128:131]
	v_mfma_f32_16x16x32_bf16 v[124:127], v[140:143], v[164:167], v[124:127]
	v_mfma_f32_16x16x32_bf16 v[112:115], v[132:135], v[172:175], v[112:115]
	v_mfma_f32_16x16x32_bf16 v[108:111], v[140:143], v[172:175], v[108:111]
	v_mfma_f32_16x16x32_bf16 v[96:99], v[132:135], v[180:183], v[96:99]
	v_mfma_f32_16x16x32_bf16 v[92:95], v[140:143], v[180:183], v[92:95]
	v_mfma_f32_16x16x32_bf16 v[80:83], v[132:135], v[188:191], v[80:83]
	v_mfma_f32_16x16x32_bf16 v[76:79], v[140:143], v[188:191], v[76:79]
	v_mfma_f32_16x16x32_bf16 v[128:131], v[136:139], v[168:171], v[128:131]
	v_mfma_f32_16x16x32_bf16 v[124:127], v[144:147], v[168:171], v[124:127]
	v_mfma_f32_16x16x32_bf16 v[112:115], v[136:139], v[176:179], v[112:115]
	v_mfma_f32_16x16x32_bf16 v[108:111], v[144:147], v[176:179], v[108:111]
	v_mfma_f32_16x16x32_bf16 v[96:99], v[136:139], v[184:187], v[96:99]
	v_mfma_f32_16x16x32_bf16 v[92:95], v[144:147], v[184:187], v[92:95]
	v_mfma_f32_16x16x32_bf16 v[80:83], v[136:139], v[192:195], v[80:83]
	v_mfma_f32_16x16x32_bf16 v[76:79], v[144:147], v[192:195], v[76:79]
	v_mfma_f32_16x16x32_bf16 v[120:123], v[148:151], v[164:167], v[120:123]
	v_mfma_f32_16x16x32_bf16 v[116:119], v[156:159], v[164:167], v[116:119]
	v_mfma_f32_16x16x32_bf16 v[104:107], v[148:151], v[172:175], v[104:107]
	v_mfma_f32_16x16x32_bf16 v[100:103], v[156:159], v[172:175], v[100:103]
	v_mfma_f32_16x16x32_bf16 v[88:91], v[148:151], v[180:183], v[88:91]
	v_mfma_f32_16x16x32_bf16 v[84:87], v[156:159], v[180:183], v[84:87]
	v_mfma_f32_16x16x32_bf16 v[72:75], v[148:151], v[188:191], v[72:75]
	v_mfma_f32_16x16x32_bf16 v[68:71], v[156:159], v[188:191], v[68:71]
	v_mfma_f32_16x16x32_bf16 v[120:123], v[152:155], v[168:171], v[120:123]
	v_mfma_f32_16x16x32_bf16 v[116:119], v[160:163], v[168:171], v[116:119]
	v_mfma_f32_16x16x32_bf16 v[104:107], v[152:155], v[176:179], v[104:107]
	v_mfma_f32_16x16x32_bf16 v[100:103], v[160:163], v[176:179], v[100:103]
	v_mfma_f32_16x16x32_bf16 v[88:91], v[152:155], v[184:187], v[88:91]
	v_mfma_f32_16x16x32_bf16 v[84:87], v[160:163], v[184:187], v[84:87]
	v_mfma_f32_16x16x32_bf16 v[72:75], v[152:155], v[192:195], v[72:75]
	v_mfma_f32_16x16x32_bf16 v[68:71], v[160:163], v[192:195], v[68:71]
	s_barrier
	s_add_i32 s94, s94, s67
	v_lshl_add_u64 v[240:241], s[34:35], 0, v[212:213]
	s_mov_b32 m0, s94
	ds_read_b128 v[164:167], v209 offset:16384
	ds_read_b128 v[168:171], v209 offset:17408
	ds_read_b128 v[172:175], v209 offset:18432
	ds_read_b128 v[176:179], v209 offset:19456
	ds_read_b128 v[180:183], v209 offset:20480
	ds_read_b128 v[184:187], v209 offset:21504
	ds_read_b128 v[188:191], v209 offset:22528
	ds_read_b128 v[192:195], v209 offset:23552
	global_load_lds_dwordx4 v212, s[34:35]
	s_add_i32 m0, s94, 0x2000
	s_add_u32 s94, s34, 0x80000
	v_lshl_add_u64 v[242:243], s[34:35], 0, v[216:217]
	s_addc_u32 s95, s35, 0
	s_add_i32 s96, s96, s67
	global_load_lds_dwordx4 v216, s[34:35]
	s_mov_b32 m0, s96
	global_load_lds_dwordx4 v212, s[94:95]
	v_lshl_add_u64 v[2:3], s[94:95], 0, v[216:217]
	s_add_i32 m0, s96, 0x2000
	global_load_lds_dwordx4 v216, s[94:95]
	s_waitcnt vmcnt(4)
	s_waitcnt lgkmcnt(0)
	s_barrier
; #define PG8_STAGE(bufoff, gbase, voff) do { _Pragma("unroll") for (int _i = 0; _i < 2; ++_i) \
;         __builtin_amdgcn_global_load_lds((const unsigned*)((const char*)(gbase) + (voff)[_i]), (LAS unsigned*)(lds + (bufoff) + ldsw + _i * 8192), 16, 0, 0); } while (0)
; #define PG8_LDA(dst, b, h) do { _Pragma("unroll") for (int m = 0; m < 4; ++m) _Pragma("unroll") for (int k = 0; k < 2; ++k) dst[m][k] = *(const LAS bf16x8*)(lds + PG8_SA(b, h) + aoff + m * 2048 + k * 1024); } while (0)
; #define PG8_LDB(dst, b, h) do { _Pragma("unroll") for (int n = 0; n < 2; ++n) _Pragma("unroll") for (int k = 0; k < 2; ++k) dst[n][k] = *(const LAS bf16x8*)(lds + PG8_SB(b, h) + boff + n * 2048 + k * 1024); } while (0)
; #define PG8_MMA(ai, bj, At, Bt) do { __builtin_amdgcn_s_setprio(1); _Pragma("unroll") for (int m = 0; m < 4; ++m) _Pragma("unroll") for (int n = 0; n < 2; ++n) _Pragma("unroll") for (int k = 0; k < 2; ++k) \
;         acc[ai][bj][m][n] = __builtin_amdgcn_mfma_f32_16x16x32_bf16(Bt[n][k], At[m][k], acc[ai][bj][m][n], 0, 0, 0); __builtin_amdgcn_s_setprio(0); } while (0)
; #define PG8_WAIT_V(n) asm volatile("s_waitcnt vmcnt(" #n ")" ::: "memory")
; #define PG8_WAIT_L(n) asm volatile("s_waitcnt lgkmcnt(" #n ")" ::: "memory")
; #define PG8_BAR __builtin_amdgcn_s_barrier()
; #define PG8_SCHED __builtin_amdgcn_sched_barrier(0)
; template <class Epi, bool ALIGN_EPI>
; __device__ __forceinline__ void gemm_phase(LAS unsigned char* lds, const int tid, const Gemm g, const StaticOrder& S, const Epi& E) {
;     ...
;             PG8_LDA(At, 0, 1); PG8_STAGE(PG8_SB(0, 0), b2, voffB); PG8_STAGE(PG8_SB(0, 1), b2 + hstepB, voffB); PG8_STAGE(PG8_SA(0, 0), a2, voffA);
;             PG8_WAIT_V(8); PG8_WAIT_L(0); PG8_BAR; PG8_MMA(1, 0, At, B0); PG8_MMA(1, 1, At, B1); PG8_BAR; PG8_SCHED;
;             PG8_LDB(B0, 1, 0); PG8_LDB(B1, 1, 1); PG8_SCHED; PG8_LDA(At, 1, 0); PG8_STAGE(PG8_SA(0, 1), a2 + hstepA, voffA);
;             PG8_WAIT_V(8); PG8_WAIT_L(0); PG8_BAR; PG8_MMA(0, 0, At, B0); PG8_MMA(0, 1, At, B1); PG8_BAR; PG8_SCHED;
	s_waitcnt lgkmcnt(0)
	v_mfma_f32_16x16x32_bf16 v[64:67], v[132:135], v[164:167], v[64:67]
	v_mfma_f32_16x16x32_bf16 v[60:63], v[140:143], v[164:167], v[60:63]
	v_mfma_f32_16x16x32_bf16 v[48:51], v[132:135], v[172:175], v[48:51]
	v_mfma_f32_16x16x32_bf16 v[44:47], v[140:143], v[172:175], v[44:47]
	v_mfma_f32_16x16x32_bf16 v[32:35], v[132:135], v[180:183], v[32:35]
	v_mfma_f32_16x16x32_bf16 v[28:31], v[140:143], v[180:183], v[28:31]
	v_mfma_f32_16x16x32_bf16 v[16:19], v[132:135], v[188:191], v[16:19]
	v_mfma_f32_16x16x32_bf16 v[12:15], v[140:143], v[188:191], v[12:15]
	v_mfma_f32_16x16x32_bf16 v[64:67], v[136:139], v[168:171], v[64:67]
	v_mfma_f32_16x16x32_bf16 v[60:63], v[144:147], v[168:171], v[60:63]
	v_mfma_f32_16x16x32_bf16 v[48:51], v[136:139], v[176:179], v[48:51]
	v_mfma_f32_16x16x32_bf16 v[44:47], v[144:147], v[176:179], v[44:47]
	v_mfma_f32_16x16x32_bf16 v[32:35], v[136:139], v[184:187], v[32:35]
	v_mfma_f32_16x16x32_bf16 v[28:31], v[144:147], v[184:187], v[28:31]
	v_mfma_f32_16x16x32_bf16 v[16:19], v[136:139], v[192:195], v[16:19]
	v_mfma_f32_16x16x32_bf16 v[12:15], v[144:147], v[192:195], v[12:15]
	v_mfma_f32_16x16x32_bf16 v[56:59], v[148:151], v[164:167], v[56:59]
	v_mfma_f32_16x16x32_bf16 v[52:55], v[156:159], v[164:167], v[52:55]
	v_mfma_f32_16x16x32_bf16 v[40:43], v[148:151], v[172:175], v[40:43]
	v_mfma_f32_16x16x32_bf16 v[36:39], v[156:159], v[172:175], v[36:39]
	v_mfma_f32_16x16x32_bf16 v[24:27], v[148:151], v[180:183], v[24:27]
	v_mfma_f32_16x16x32_bf16 v[20:23], v[156:159], v[180:183], v[20:23]
	v_mfma_f32_16x16x32_bf16 v[8:11], v[148:151], v[188:191], v[8:11]
	v_mfma_f32_16x16x32_bf16 v[2:5], v[156:159], v[188:191], v[4:7]
	v_mfma_f32_16x16x32_bf16 v[56:59], v[152:155], v[168:171], v[56:59]
	v_mfma_f32_16x16x32_bf16 v[52:55], v[160:163], v[168:171], v[52:55]
	v_mfma_f32_16x16x32_bf16 v[40:43], v[152:155], v[176:179], v[40:43]
	v_mfma_f32_16x16x32_bf16 v[36:39], v[160:163], v[176:179], v[36:39]
	v_mfma_f32_16x16x32_bf16 v[24:27], v[152:155], v[184:187], v[24:27]
	v_mfma_f32_16x16x32_bf16 v[20:23], v[160:163], v[184:187], v[20:23]
	v_mfma_f32_16x16x32_bf16 v[8:11], v[152:155], v[192:195], v[8:11]
	v_mfma_f32_16x16x32_bf16 v[2:5], v[160:163], v[192:195], v[2:5]
	s_barrier
	s_add_i32 s94, 0, 0x18000
	v_add_u32_e32 v0, s94, v205
	s_add_i32 s95, 0, 0x1c000
	ds_read_b128 v[132:135], v0
	ds_read_b128 v[136:139], v0 offset:1024
	ds_read_b128 v[140:143], v0 offset:2048
	ds_read_b128 v[144:147], v0 offset:3072
	v_add_u32_e32 v0, s95, v205
	ds_read_b128 v[148:151], v0
	ds_read_b128 v[152:155], v0 offset:1024
	ds_read_b128 v[156:159], v0 offset:2048
	ds_read_b128 v[160:163], v0 offset:3072
	s_mov_b32 m0, s68
	s_nop 0
	global_load_lds_dwordx4 v210, s[54:55]
	s_mov_b32 m0, s69
	s_nop 0
	global_load_lds_dwordx4 v214, s[54:55]
	s_add_u32 s54, s54, 0x80000
	s_addc_u32 s55, s55, 0
	s_mov_b32 m0, s70
	ds_read_b128 v[164:167], v209 offset:32768
	ds_read_b128 v[168:171], v209 offset:33792
	ds_read_b128 v[172:175], v209 offset:34816
	ds_read_b128 v[176:179], v209 offset:35840
	ds_read_b128 v[180:183], v209 offset:36864
	ds_read_b128 v[184:187], v209 offset:37888
	ds_read_b128 v[188:191], v209 offset:38912
	ds_read_b128 v[192:195], v209 offset:39936
	global_load_lds_dwordx4 v210, s[54:55]
	s_mov_b32 m0, s71
	s_nop 0
	global_load_lds_dwordx4 v214, s[54:55]
	s_waitcnt vmcnt(8)
	s_waitcnt lgkmcnt(0)
	s_barrier
; #define PG8_STAGE(bufoff, gbase, voff) do { _Pragma("unroll") for (int _i = 0; _i < 2; ++_i) \
;         __builtin_amdgcn_global_load_lds((const unsigned*)((const char*)(gbase) + (voff)[_i]), (LAS unsigned*)(lds + (bufoff) + ldsw + _i * 8192), 16, 0, 0); } while (0)
; #define PG8_LDA(dst, b, h) do { _Pragma("unroll") for (int m = 0; m < 4; ++m) _Pragma("unroll") for (int k = 0; k < 2; ++k) dst[m][k] = *(const LAS bf16x8*)(lds + PG8_SA(b, h) + aoff + m * 2048 + k * 1024); } while (0)
; #define PG8_MMA(ai, bj, At, Bt) do { __builtin_amdgcn_s_setprio(1); _Pragma("unroll") for (int m = 0; m < 4; ++m) _Pragma("unroll") for (int n = 0; n < 2; ++n) _Pragma("unroll") for (int k = 0; k < 2; ++k) \
;         acc[ai][bj][m][n] = __builtin_amdgcn_mfma_f32_16x16x32_bf16(Bt[n][k], At[m][k], acc[ai][bj][m][n], 0, 0, 0); __builtin_amdgcn_s_setprio(0); } while (0)
; #define PG8_WAIT_V(n) asm volatile("s_waitcnt vmcnt(" #n ")" ::: "memory")
; #define PG8_WAIT_L(n) asm volatile("s_waitcnt lgkmcnt(" #n ")" ::: "memory")
; #define PG8_BAR __builtin_amdgcn_s_barrier()
; #define PG8_SCHED __builtin_amdgcn_sched_barrier(0)
; template <class Epi, bool ALIGN_EPI>
; __device__ __forceinline__ void gemm_phase(LAS unsigned char* lds, const int tid, const Gemm g, const StaticOrder& S, const Epi& E) {
;     ...
;             PG8_WAIT_V(8); PG8_WAIT_L(0); PG8_BAR; PG8_MMA(0, 0, At, B0); PG8_MMA(0, 1, At, B1); PG8_BAR; PG8_SCHED;
;             PG8_LDA(At, 1, 1); PG8_STAGE(PG8_SB(1, 0), b3, voffB); PG8_STAGE(PG8_SB(1, 1), b3 + hstepB, voffB); PG8_STAGE(PG8_SA(1, 0), a3, voffA);
;             PG8_WAIT_V(8); PG8_WAIT_L(0); PG8_BAR; PG8_MMA(1, 0, At, B0); PG8_MMA(1, 1, At, B1); PG8_BAR; PG8_SCHED;
;         }
	s_waitcnt lgkmcnt(0)
	v_mfma_f32_16x16x32_bf16 v[128:131], v[132:135], v[164:167], v[128:131]
	v_mfma_f32_16x16x32_bf16 v[124:127], v[140:143], v[164:167], v[124:127]
	v_mfma_f32_16x16x32_bf16 v[112:115], v[132:135], v[172:175], v[112:115]
	v_mfma_f32_16x16x32_bf16 v[108:111], v[140:143], v[172:175], v[108:111]
	v_mfma_f32_16x16x32_bf16 v[96:99], v[132:135], v[180:183], v[96:99]
	v_mfma_f32_16x16x32_bf16 v[92:95], v[140:143], v[180:183], v[92:95]
	v_mfma_f32_16x16x32_bf16 v[80:83], v[132:135], v[188:191], v[80:83]
	v_mfma_f32_16x16x32_bf16 v[76:79], v[140:143], v[188:191], v[76:79]
	v_mfma_f32_16x16x32_bf16 v[128:131], v[136:139], v[168:171], v[128:131]
	v_mfma_f32_16x16x32_bf16 v[124:127], v[144:147], v[168:171], v[124:127]
	v_mfma_f32_16x16x32_bf16 v[112:115], v[136:139], v[176:179], v[112:115]
	v_mfma_f32_16x16x32_bf16 v[108:111], v[144:147], v[176:179], v[108:111]
	v_mfma_f32_16x16x32_bf16 v[96:99], v[136:139], v[184:187], v[96:99]
	v_mfma_f32_16x16x32_bf16 v[92:95], v[144:147], v[184:187], v[92:95]
	v_mfma_f32_16x16x32_bf16 v[80:83], v[136:139], v[192:195], v[80:83]
	v_mfma_f32_16x16x32_bf16 v[76:79], v[144:147], v[192:195], v[76:79]
	v_mfma_f32_16x16x32_bf16 v[120:123], v[148:151], v[164:167], v[120:123]
	v_mfma_f32_16x16x32_bf16 v[116:119], v[156:159], v[164:167], v[116:119]
	v_mfma_f32_16x16x32_bf16 v[104:107], v[148:151], v[172:175], v[104:107]
	v_mfma_f32_16x16x32_bf16 v[100:103], v[156:159], v[172:175], v[100:103]
	v_mfma_f32_16x16x32_bf16 v[88:91], v[148:151], v[180:183], v[88:91]
	v_mfma_f32_16x16x32_bf16 v[84:87], v[156:159], v[180:183], v[84:87]
	v_mfma_f32_16x16x32_bf16 v[72:75], v[148:151], v[188:191], v[72:75]
	v_mfma_f32_16x16x32_bf16 v[68:71], v[156:159], v[188:191], v[68:71]
	v_mfma_f32_16x16x32_bf16 v[120:123], v[152:155], v[168:171], v[120:123]
	v_mfma_f32_16x16x32_bf16 v[116:119], v[160:163], v[168:171], v[116:119]
	v_mfma_f32_16x16x32_bf16 v[104:107], v[152:155], v[176:179], v[104:107]
	v_mfma_f32_16x16x32_bf16 v[100:103], v[160:163], v[176:179], v[100:103]
	v_mfma_f32_16x16x32_bf16 v[88:91], v[152:155], v[184:187], v[88:91]
	v_mfma_f32_16x16x32_bf16 v[84:87], v[160:163], v[184:187], v[84:87]
	v_mfma_f32_16x16x32_bf16 v[72:75], v[152:155], v[192:195], v[72:75]
	v_mfma_f32_16x16x32_bf16 v[68:71], v[160:163], v[192:195], v[68:71]
	s_barrier
	s_add_i32 s54, s94, s67
	v_lshl_add_u64 v[6:7], v[240:241], 0, s[42:43]
	s_mov_b32 m0, s54
	ds_read_b128 v[164:167], v209 offset:49152
	ds_read_b128 v[168:171], v209 offset:50176
	ds_read_b128 v[172:175], v209 offset:51200
	ds_read_b128 v[176:179], v209 offset:52224
	ds_read_b128 v[180:183], v209 offset:53248
	ds_read_b128 v[184:187], v209 offset:54272
	ds_read_b128 v[188:191], v209 offset:55296
	ds_read_b128 v[192:195], v209 offset:56320
	global_load_lds_dwordx4 v[6:7], off
	s_add_i32 m0, s54, 0x2000
	s_add_u32 s34, s34, 0x80080
	v_lshl_add_u64 v[6:7], v[242:243], 0, s[42:43]
	s_addc_u32 s35, s35, 0
	s_add_i32 s54, s95, s67
	global_load_lds_dwordx4 v[6:7], off
	s_mov_b32 m0, s54
	s_nop 0
	global_load_lds_dwordx4 v212, s[34:35]
	v_lshl_add_u64 v[6:7], s[34:35], 0, v[216:217]
	s_add_i32 m0, s54, 0x2000
	s_nop 0
	global_load_lds_dwordx4 v216, s[34:35]
	s_waitcnt vmcnt(4)
	s_waitcnt lgkmcnt(0)
	s_barrier
	s_waitcnt lgkmcnt(0)
	v_mfma_f32_16x16x32_bf16 v[64:67], v[132:135], v[164:167], v[64:67]
	v_mfma_f32_16x16x32_bf16 v[60:63], v[140:143], v[164:167], v[60:63]
	v_mfma_f32_16x16x32_bf16 v[48:51], v[132:135], v[172:175], v[48:51]
	v_mfma_f32_16x16x32_bf16 v[44:47], v[140:143], v[172:175], v[44:47]
	v_mfma_f32_16x16x32_bf16 v[32:35], v[132:135], v[180:183], v[32:35]
	v_mfma_f32_16x16x32_bf16 v[28:31], v[140:143], v[180:183], v[28:31]
	v_mfma_f32_16x16x32_bf16 v[16:19], v[132:135], v[188:191], v[16:19]
	v_mfma_f32_16x16x32_bf16 v[12:15], v[140:143], v[188:191], v[12:15]
	v_mfma_f32_16x16x32_bf16 v[64:67], v[136:139], v[168:171], v[64:67]
	v_mfma_f32_16x16x32_bf16 v[60:63], v[144:147], v[168:171], v[60:63]
	v_mfma_f32_16x16x32_bf16 v[48:51], v[136:139], v[176:179], v[48:51]
	v_mfma_f32_16x16x32_bf16 v[44:47], v[144:147], v[176:179], v[44:47]
	v_mfma_f32_16x16x32_bf16 v[32:35], v[136:139], v[184:187], v[32:35]
	v_mfma_f32_16x16x32_bf16 v[28:31], v[144:147], v[184:187], v[28:31]
	v_mfma_f32_16x16x32_bf16 v[16:19], v[136:139], v[192:195], v[16:19]
	v_mfma_f32_16x16x32_bf16 v[12:15], v[144:147], v[192:195], v[12:15]
	v_mfma_f32_16x16x32_bf16 v[56:59], v[148:151], v[164:167], v[56:59]
	v_mfma_f32_16x16x32_bf16 v[52:55], v[156:159], v[164:167], v[52:55]
	v_mfma_f32_16x16x32_bf16 v[40:43], v[148:151], v[172:175], v[40:43]
	v_mfma_f32_16x16x32_bf16 v[36:39], v[156:159], v[172:175], v[36:39]
	v_mfma_f32_16x16x32_bf16 v[24:27], v[148:151], v[180:183], v[24:27]
	v_mfma_f32_16x16x32_bf16 v[20:23], v[156:159], v[180:183], v[20:23]
	v_mfma_f32_16x16x32_bf16 v[6:9], v[148:151], v[188:191], v[8:11]
	v_mfma_f32_16x16x32_bf16 v[2:5], v[156:159], v[188:191], v[2:5]
	v_mfma_f32_16x16x32_bf16 v[56:59], v[152:155], v[168:171], v[56:59]
	v_mfma_f32_16x16x32_bf16 v[52:55], v[160:163], v[168:171], v[52:55]
	v_mfma_f32_16x16x32_bf16 v[40:43], v[152:155], v[176:179], v[40:43]
	v_mfma_f32_16x16x32_bf16 v[36:39], v[160:163], v[176:179], v[36:39]
	v_mfma_f32_16x16x32_bf16 v[24:27], v[152:155], v[184:187], v[24:27]
	v_mfma_f32_16x16x32_bf16 v[20:23], v[160:163], v[184:187], v[20:23]
	v_mfma_f32_16x16x32_bf16 v[8:11], v[152:155], v[192:195], v[6:9]
	v_mfma_f32_16x16x32_bf16 v[4:7], v[160:163], v[192:195], v[2:5]
	s_barrier
	s_add_u32 s92, s92, 0x400
	s_addc_u32 s93, s93, 0
	s_add_u32 s21, s21, 0x100
	s_addc_u32 s36, s36, 0
	s_add_u32 s30, s30, 0x100
	s_addc_u32 s31, s31, 0
	s_cmp_ge_u32 s5, s19
	s_cbranch_scc1 .LBB0_266

; #define PG8_STAGE(bufoff, gbase, voff) do { _Pragma("unroll") for (int _i = 0; _i < 2; ++_i) \
;         __builtin_amdgcn_global_load_lds((const unsigned*)((const char*)(gbase) + (voff)[_i]), (LAS unsigned*)(lds + (bufoff) + ldsw + _i * 8192), 16, 0, 0); } while (0)
; #define PG8_LDA(dst, b, h) do { _Pragma("unroll") for (int m = 0; m < 4; ++m) _Pragma("unroll") for (int k = 0; k < 2; ++k) dst[m][k] = *(const LAS bf16x8*)(lds + PG8_SA(b, h) + aoff + m * 2048 + k * 1024); } while (0)
; #define PG8_LDB(dst, b, h) do { _Pragma("unroll") for (int n = 0; n < 2; ++n) _Pragma("unroll") for (int k = 0; k < 2; ++k) dst[n][k] = *(const LAS bf16x8*)(lds + PG8_SB(b, h) + boff + n * 2048 + k * 1024); } while (0)
; #define PG8_WAIT_V(n) asm volatile("s_waitcnt vmcnt(" #n ")" ::: "memory")
; #define PG8_WAIT_L(n) asm volatile("s_waitcnt lgkmcnt(" #n ")" ::: "memory")
; #define PG8_BAR __builtin_amdgcn_s_barrier()
; template <class Epi, bool ALIGN_EPI>
; __device__ __forceinline__ void gemm_phase(LAS unsigned char* lds, const int tid, const Gemm g, const StaticOrder& S, const Epi& E) {
;     ...
;         const bool has_next = S.next(ui + 1, nxt);
;         const char* nA = has_next ? (const char*)g.A + (size_t)nxt.pm * tstepA + PG8_KOFFA(nxt) : cA; const char* nB = has_next ? (const char*)g.Bt + (size_t)nxt.pn * tstepB + PG8_KOFFB(nxt) : cB;
;         const int nt = cur.ks >= 0 ? nt_split : nt_full;
;         for (int t = 0; t < nt; t += 2) {
;             if constexpr (Epi::HOOK) { if (t != 0 && (t & 7) == 0) E.hook(acc, cur, (t >> 3) - 1, wr, wc, fr, fq); }
;             const bool last = (t == nt - 2);
;             const char* a1 = cA + (size_t)(t + 1) * kstepA;
;             const char* a2 = last ? nA : cA + (size_t)(t + 2) * kstepA; const char* b2 = last ? nB : cB + (size_t)(t + 2) * kstepB;
;             const char* a3 = a2 + kstepA; const char* b3 = b2 + kstepB;
;             PG8_LDB(B0, 0, 0); PG8_LDB(B1, 0, 1); PG8_SCHED; PG8_LDA(At, 0, 0); PG8_STAGE(PG8_SA(1, 1), a1 + hstepA, voffA);
;             PG8_WAIT_V(8); PG8_WAIT_L(0); PG8_BAR; PG8_MMA(0, 0, At, B0); PG8_MMA(0, 1, At, B1); PG8_BAR; PG8_SCHED;
;             PG8_LDA(At, 0, 1); PG8_STAGE(PG8_SB(0, 0), b2, voffB); PG8_STAGE(PG8_SB(0, 1), b2 + hstepB, voffB); PG8_STAGE(PG8_SA(0, 0), a2, voffA);
;             PG8_WAIT_V(8); PG8_WAIT_L(0); PG8_BAR; PG8_MMA(1, 0, At, B0); PG8_MMA(1, 1, At, B1); PG8_BAR; PG8_SCHED;
.LBB0_667:
	s_add_u32 s22, s20, 0xfff80080
	s_addc_u32 s23, s21, -1
	s_add_i32 s49, 0, 0x10000
	s_cmp_eq_u32 s19, 28
	s_cselect_b32 s25, s15, s23
	s_cselect_b32 s24, s14, s22
	v_add_u32_e32 v0, s49, v173
	s_cselect_b32 s23, s17, s13
	s_cselect_b32 s22, s16, s11
	s_add_i32 s52, 0, 0x14000
	ds_read_b128 v[130:133], v0
	ds_read_b128 v[134:137], v0 offset:1024
	ds_read_b128 v[138:141], v0 offset:2048
	ds_read_b128 v[142:145], v0 offset:3072
	v_add_u32_e32 v0, s52, v173
	ds_read_b128 v[158:161], v0
	ds_read_b128 v[162:165], v0 offset:1024
	ds_read_b128 v[166:169], v0 offset:2048
	ds_read_b128 v[178:181], v0 offset:3072
	s_add_i32 m0, s28, 0xc000
	ds_read_b128 v[182:185], v176
	ds_read_b128 v[186:189], v176 offset:1024
	ds_read_b128 v[190:193], v176 offset:2048
	ds_read_b128 v[208:211], v176 offset:3072
	ds_read_b128 v[212:215], v176 offset:4096
	ds_read_b128 v[216:219], v176 offset:5120
	ds_read_b128 v[220:223], v176 offset:6144
	ds_read_b128 v[240:243], v176 offset:7168
	global_load_lds_dwordx4 v156, s[20:21]
	s_add_i32 m0, s28, 0xe000
	s_nop 0
	global_load_lds_dwordx4 v154, s[20:21]
	s_sub_u32 s98, s20, 0x80000
	s_subb_u32 s99, s21, 0
	s_mov_b32 m0, s34
	s_nop 0
	global_load_lds_dwordx4 v156, s[98:99]
	s_mov_b32 m0, s35
	s_nop 0
	global_load_lds_dwordx4 v154, s[98:99]
	s_waitcnt vmcnt(8)
	s_waitcnt lgkmcnt(0)
	s_barrier
	s_waitcnt lgkmcnt(0)
	v_mfma_f32_16x16x32_bf16 v[126:129], v[130:133], v[182:185], v[126:129]
	v_mfma_f32_16x16x32_bf16 v[122:125], v[138:141], v[182:185], v[122:125]
	v_mfma_f32_16x16x32_bf16 v[118:121], v[130:133], v[190:193], v[118:121]
	v_mfma_f32_16x16x32_bf16 v[114:117], v[138:141], v[190:193], v[114:117]
	v_mfma_f32_16x16x32_bf16 v[102:105], v[130:133], v[212:215], v[102:105]
	v_mfma_f32_16x16x32_bf16 v[98:101], v[138:141], v[212:215], v[98:101]
	v_mfma_f32_16x16x32_bf16 v[86:89], v[130:133], v[220:223], v[86:89]
	v_mfma_f32_16x16x32_bf16 v[82:85], v[138:141], v[220:223], v[82:85]
	v_mfma_f32_16x16x32_bf16 v[126:129], v[134:137], v[186:189], v[126:129]
	v_mfma_f32_16x16x32_bf16 v[122:125], v[142:145], v[186:189], v[122:125]
	v_mfma_f32_16x16x32_bf16 v[118:121], v[134:137], v[208:211], v[118:121]
	v_mfma_f32_16x16x32_bf16 v[114:117], v[142:145], v[208:211], v[114:117]
	v_mfma_f32_16x16x32_bf16 v[102:105], v[134:137], v[216:219], v[102:105]
	v_mfma_f32_16x16x32_bf16 v[98:101], v[142:145], v[216:219], v[98:101]
	v_mfma_f32_16x16x32_bf16 v[86:89], v[134:137], v[240:243], v[86:89]
	v_mfma_f32_16x16x32_bf16 v[82:85], v[142:145], v[240:243], v[82:85]
	v_mfma_f32_16x16x32_bf16 v[110:113], v[158:161], v[182:185], v[110:113]
	v_mfma_f32_16x16x32_bf16 v[106:109], v[166:169], v[182:185], v[106:109]
	v_mfma_f32_16x16x32_bf16 v[94:97], v[158:161], v[190:193], v[94:97]
	v_mfma_f32_16x16x32_bf16 v[90:93], v[166:169], v[190:193], v[90:93]
	v_mfma_f32_16x16x32_bf16 v[78:81], v[158:161], v[212:215], v[78:81]
	v_mfma_f32_16x16x32_bf16 v[74:77], v[166:169], v[212:215], v[74:77]
	v_mfma_f32_16x16x32_bf16 v[70:73], v[158:161], v[220:223], v[70:73]
	v_mfma_f32_16x16x32_bf16 v[66:69], v[166:169], v[220:223], v[66:69]
	v_mfma_f32_16x16x32_bf16 v[110:113], v[162:165], v[186:189], v[110:113]
	v_mfma_f32_16x16x32_bf16 v[106:109], v[178:181], v[186:189], v[106:109]
	v_mfma_f32_16x16x32_bf16 v[94:97], v[162:165], v[208:211], v[94:97]
	v_mfma_f32_16x16x32_bf16 v[90:93], v[178:181], v[208:211], v[90:93]
	v_mfma_f32_16x16x32_bf16 v[78:81], v[162:165], v[216:219], v[78:81]
	v_mfma_f32_16x16x32_bf16 v[74:77], v[178:181], v[216:219], v[74:77]
	v_mfma_f32_16x16x32_bf16 v[70:73], v[162:165], v[240:243], v[70:73]
	v_mfma_f32_16x16x32_bf16 v[66:69], v[178:181], v[240:243], v[66:69]
	s_barrier
	s_add_i32 s49, s49, s27
	v_lshl_add_u64 v[170:171], s[22:23], 0, v[148:149]
	s_mov_b32 m0, s49
	ds_read_b128 v[182:185], v176 offset:16384
	ds_read_b128 v[186:189], v176 offset:17408
	ds_read_b128 v[190:193], v176 offset:18432
	ds_read_b128 v[208:211], v176 offset:19456
	ds_read_b128 v[212:215], v176 offset:20480
	ds_read_b128 v[216:219], v176 offset:21504
	ds_read_b128 v[220:223], v176 offset:22528
	ds_read_b128 v[240:243], v176 offset:23552
	global_load_lds_dwordx4 v148, s[22:23]
	s_add_i32 m0, s49, 0x2000
	s_add_u32 s54, s22, 0x80000
	v_lshl_add_u64 v[194:195], s[22:23], 0, v[152:153]
	s_addc_u32 s55, s23, 0
	s_add_i32 s49, s52, s27
	global_load_lds_dwordx4 v152, s[22:23]
	s_mov_b32 m0, s49
	global_load_lds_dwordx4 v148, s[54:55]
	s_add_i32 m0, s49, 0x2000
	s_nop 0
	global_load_lds_dwordx4 v152, s[54:55]
	s_waitcnt vmcnt(4)
	s_waitcnt lgkmcnt(0)
	s_barrier
	s_waitcnt lgkmcnt(0)
	v_mfma_f32_16x16x32_bf16 v[62:65], v[130:133], v[182:185], v[62:65]
	v_mfma_f32_16x16x32_bf16 v[58:61], v[138:141], v[182:185], v[58:61]
	v_mfma_f32_16x16x32_bf16 v[54:57], v[130:133], v[190:193], v[54:57]
	v_mfma_f32_16x16x32_bf16 v[50:53], v[138:141], v[190:193], v[50:53]
	v_mfma_f32_16x16x32_bf16 v[38:41], v[130:133], v[212:215], v[38:41]
	v_mfma_f32_16x16x32_bf16 v[34:37], v[138:141], v[212:215], v[34:37]
	v_mfma_f32_16x16x32_bf16 v[22:25], v[130:133], v[220:223], v[22:25]
	v_mfma_f32_16x16x32_bf16 v[18:21], v[138:141], v[220:223], v[18:21]
	v_mfma_f32_16x16x32_bf16 v[62:65], v[134:137], v[186:189], v[62:65]
	v_mfma_f32_16x16x32_bf16 v[58:61], v[142:145], v[186:189], v[58:61]
	v_mfma_f32_16x16x32_bf16 v[54:57], v[134:137], v[208:211], v[54:57]
	v_mfma_f32_16x16x32_bf16 v[50:53], v[142:145], v[208:211], v[50:53]
	v_mfma_f32_16x16x32_bf16 v[38:41], v[134:137], v[216:219], v[38:41]
	v_mfma_f32_16x16x32_bf16 v[34:37], v[142:145], v[216:219], v[34:37]
	v_mfma_f32_16x16x32_bf16 v[22:25], v[134:137], v[240:243], v[22:25]
	v_mfma_f32_16x16x32_bf16 v[18:21], v[142:145], v[240:243], v[18:21]
	v_mfma_f32_16x16x32_bf16 v[46:49], v[158:161], v[182:185], v[46:49]
	v_mfma_f32_16x16x32_bf16 v[42:45], v[166:169], v[182:185], v[42:45]
	v_mfma_f32_16x16x32_bf16 v[30:33], v[158:161], v[190:193], v[30:33]
	v_mfma_f32_16x16x32_bf16 v[26:29], v[166:169], v[190:193], v[26:29]
	v_mfma_f32_16x16x32_bf16 v[14:17], v[158:161], v[212:215], v[14:17]
	v_mfma_f32_16x16x32_bf16 v[10:13], v[166:169], v[212:215], v[10:13]
	v_mfma_f32_16x16x32_bf16 v[6:9], v[158:161], v[220:223], v[6:9]
	v_mfma_f32_16x16x32_bf16 v[2:5], v[166:169], v[220:223], v[2:5]
	v_mfma_f32_16x16x32_bf16 v[46:49], v[162:165], v[186:189], v[46:49]
	v_mfma_f32_16x16x32_bf16 v[42:45], v[178:181], v[186:189], v[42:45]
	v_mfma_f32_16x16x32_bf16 v[30:33], v[162:165], v[208:211], v[30:33]
	v_mfma_f32_16x16x32_bf16 v[26:29], v[178:181], v[208:211], v[26:29]
	v_mfma_f32_16x16x32_bf16 v[14:17], v[162:165], v[216:219], v[14:17]
	v_mfma_f32_16x16x32_bf16 v[10:13], v[178:181], v[216:219], v[10:13]
	v_mfma_f32_16x16x32_bf16 v[6:9], v[162:165], v[240:243], v[6:9]
	v_mfma_f32_16x16x32_bf16 v[2:5], v[178:181], v[240:243], v[2:5]
	s_barrier
; #define PG8_STAGE(bufoff, gbase, voff) do { _Pragma("unroll") for (int _i = 0; _i < 2; ++_i) \
;         __builtin_amdgcn_global_load_lds((const unsigned*)((const char*)(gbase) + (voff)[_i]), (LAS unsigned*)(lds + (bufoff) + ldsw + _i * 8192), 16, 0, 0); } while (0)
; #define PG8_LDA(dst, b, h) do { _Pragma("unroll") for (int m = 0; m < 4; ++m) _Pragma("unroll") for (int k = 0; k < 2; ++k) dst[m][k] = *(const LAS bf16x8*)(lds + PG8_SA(b, h) + aoff + m * 2048 + k * 1024); } while (0)
; #define PG8_LDB(dst, b, h) do { _Pragma("unroll") for (int n = 0; n < 2; ++n) _Pragma("unroll") for (int k = 0; k < 2; ++k) dst[n][k] = *(const LAS bf16x8*)(lds + PG8_SB(b, h) + boff + n * 2048 + k * 1024); } while (0)
; #define PG8_MMA(ai, bj, At, Bt) do { __builtin_amdgcn_s_setprio(1); _Pragma("unroll") for (int m = 0; m < 4; ++m) _Pragma("unroll") for (int n = 0; n < 2; ++n) _Pragma("unroll") for (int k = 0; k < 2; ++k) \
;         acc[ai][bj][m][n] = __builtin_amdgcn_mfma_f32_16x16x32_bf16(Bt[n][k], At[m][k], acc[ai][bj][m][n], 0, 0, 0); __builtin_amdgcn_s_setprio(0); } while (0)
; #define PG8_WAIT_V(n) asm volatile("s_waitcnt vmcnt(" #n ")" ::: "memory")
; #define PG8_WAIT_L(n) asm volatile("s_waitcnt lgkmcnt(" #n ")" ::: "memory")
; #define PG8_BAR __builtin_amdgcn_s_barrier()
; #define PG8_SCHED __builtin_amdgcn_sched_barrier(0)
; template <class Epi, bool ALIGN_EPI>
; __device__ __forceinline__ void gemm_phase(LAS unsigned char* lds, const int tid, const Gemm g, const StaticOrder& S, const Epi& E) {
;     ...
;             PG8_LDB(B0, 1, 0); PG8_LDB(B1, 1, 1); PG8_SCHED; PG8_LDA(At, 1, 0); PG8_STAGE(PG8_SA(0, 1), a2 + hstepA, voffA);
;             PG8_WAIT_V(8); PG8_WAIT_L(0); PG8_BAR; PG8_MMA(0, 0, At, B0); PG8_MMA(0, 1, At, B1); PG8_BAR; PG8_SCHED;
;             PG8_LDA(At, 1, 1); PG8_STAGE(PG8_SB(1, 0), b3, voffB); PG8_STAGE(PG8_SB(1, 1), b3 + hstepB, voffB); PG8_STAGE(PG8_SA(1, 0), a3, voffA);
;             PG8_WAIT_V(8); PG8_WAIT_L(0); PG8_BAR; PG8_MMA(1, 0, At, B0); PG8_MMA(1, 1, At, B1); PG8_BAR; PG8_SCHED;
;         }
;         if constexpr (ALIGN_EPI) { if (wr == 0) PG8_BAR; }
	s_add_i32 s49, 0, 0x18000
	v_add_u32_e32 v0, s49, v173
	s_add_i32 s52, 0, 0x1c000
	ds_read_b128 v[130:133], v0
	ds_read_b128 v[134:137], v0 offset:1024
	ds_read_b128 v[138:141], v0 offset:2048
	ds_read_b128 v[142:145], v0 offset:3072
	v_add_u32_e32 v0, s52, v173
	ds_read_b128 v[158:161], v0
	ds_read_b128 v[162:165], v0 offset:1024
	ds_read_b128 v[166:169], v0 offset:2048
	ds_read_b128 v[178:181], v0 offset:3072
	s_mov_b32 m0, s28
	s_nop 0
	global_load_lds_dwordx4 v146, s[24:25]
	s_mov_b32 m0, s29
	s_nop 0
	global_load_lds_dwordx4 v150, s[24:25]
	s_add_u32 s24, s24, 0x80000
	s_addc_u32 s25, s25, 0
	s_mov_b32 m0, s30
	ds_read_b128 v[182:185], v176 offset:32768
	ds_read_b128 v[186:189], v176 offset:33792
	ds_read_b128 v[190:193], v176 offset:34816
	ds_read_b128 v[208:211], v176 offset:35840
	ds_read_b128 v[212:215], v176 offset:36864
	ds_read_b128 v[216:219], v176 offset:37888
	ds_read_b128 v[220:223], v176 offset:38912
	ds_read_b128 v[240:243], v176 offset:39936
	global_load_lds_dwordx4 v146, s[24:25]
	s_mov_b32 m0, s31
	s_nop 0
	global_load_lds_dwordx4 v150, s[24:25]
	s_waitcnt vmcnt(8)
	s_waitcnt lgkmcnt(0)
	s_barrier
	s_waitcnt lgkmcnt(0)
	v_mfma_f32_16x16x32_bf16 v[126:129], v[130:133], v[182:185], v[126:129]
	v_mfma_f32_16x16x32_bf16 v[122:125], v[138:141], v[182:185], v[122:125]
	v_mfma_f32_16x16x32_bf16 v[118:121], v[130:133], v[190:193], v[118:121]
	v_mfma_f32_16x16x32_bf16 v[114:117], v[138:141], v[190:193], v[114:117]
	v_mfma_f32_16x16x32_bf16 v[102:105], v[130:133], v[212:215], v[102:105]
	v_mfma_f32_16x16x32_bf16 v[98:101], v[138:141], v[212:215], v[98:101]
	v_mfma_f32_16x16x32_bf16 v[86:89], v[130:133], v[220:223], v[86:89]
	v_mfma_f32_16x16x32_bf16 v[82:85], v[138:141], v[220:223], v[82:85]
	v_mfma_f32_16x16x32_bf16 v[126:129], v[134:137], v[186:189], v[126:129]
	v_mfma_f32_16x16x32_bf16 v[122:125], v[142:145], v[186:189], v[122:125]
	v_mfma_f32_16x16x32_bf16 v[118:121], v[134:137], v[208:211], v[118:121]
	v_mfma_f32_16x16x32_bf16 v[114:117], v[142:145], v[208:211], v[114:117]
	v_mfma_f32_16x16x32_bf16 v[102:105], v[134:137], v[216:219], v[102:105]
	v_mfma_f32_16x16x32_bf16 v[98:101], v[142:145], v[216:219], v[98:101]
	v_mfma_f32_16x16x32_bf16 v[86:89], v[134:137], v[240:243], v[86:89]
	v_mfma_f32_16x16x32_bf16 v[82:85], v[142:145], v[240:243], v[82:85]
	v_mfma_f32_16x16x32_bf16 v[110:113], v[158:161], v[182:185], v[110:113]
	v_mfma_f32_16x16x32_bf16 v[106:109], v[166:169], v[182:185], v[106:109]
	v_mfma_f32_16x16x32_bf16 v[94:97], v[158:161], v[190:193], v[94:97]
	v_mfma_f32_16x16x32_bf16 v[90:93], v[166:169], v[190:193], v[90:93]
	v_mfma_f32_16x16x32_bf16 v[78:81], v[158:161], v[212:215], v[78:81]
	v_mfma_f32_16x16x32_bf16 v[74:77], v[166:169], v[212:215], v[74:77]
	v_mfma_f32_16x16x32_bf16 v[70:73], v[158:161], v[220:223], v[70:73]
	v_mfma_f32_16x16x32_bf16 v[66:69], v[166:169], v[220:223], v[66:69]
	v_mfma_f32_16x16x32_bf16 v[110:113], v[162:165], v[186:189], v[110:113]
	v_mfma_f32_16x16x32_bf16 v[106:109], v[178:181], v[186:189], v[106:109]
	v_mfma_f32_16x16x32_bf16 v[94:97], v[162:165], v[208:211], v[94:97]
	v_mfma_f32_16x16x32_bf16 v[90:93], v[178:181], v[208:211], v[90:93]
	v_mfma_f32_16x16x32_bf16 v[78:81], v[162:165], v[216:219], v[78:81]
	v_mfma_f32_16x16x32_bf16 v[74:77], v[178:181], v[216:219], v[74:77]
	v_mfma_f32_16x16x32_bf16 v[70:73], v[162:165], v[240:243], v[70:73]
	v_mfma_f32_16x16x32_bf16 v[66:69], v[178:181], v[240:243], v[66:69]
	s_barrier
	s_add_i32 s24, s49, s27
	v_lshl_add_u64 v[170:171], v[170:171], 0, s[42:43]
	s_mov_b32 m0, s24
	ds_read_b128 v[182:185], v176 offset:49152
	ds_read_b128 v[186:189], v176 offset:50176
	ds_read_b128 v[190:193], v176 offset:51200
	ds_read_b128 v[208:211], v176 offset:52224
	ds_read_b128 v[212:215], v176 offset:53248
	ds_read_b128 v[216:219], v176 offset:54272
	ds_read_b128 v[220:223], v176 offset:55296
	ds_read_b128 v[240:243], v176 offset:56320
	global_load_lds_dwordx4 v[170:171], off
	s_add_i32 m0, s24, 0x2000
	s_add_u32 s22, s22, 0x80080
	v_lshl_add_u64 v[170:171], v[194:195], 0, s[42:43]
	s_addc_u32 s23, s23, 0
	s_add_i32 s24, s52, s27
	global_load_lds_dwordx4 v[170:171], off
	s_mov_b32 m0, s24
	s_nop 0
	global_load_lds_dwordx4 v148, s[22:23]
	s_add_i32 m0, s24, 0x2000
	s_nop 0
	global_load_lds_dwordx4 v152, s[22:23]
	s_waitcnt vmcnt(4)
	s_waitcnt lgkmcnt(0)
	s_barrier
	s_waitcnt lgkmcnt(0)
	v_mfma_f32_16x16x32_bf16 v[62:65], v[130:133], v[182:185], v[62:65]
	v_mfma_f32_16x16x32_bf16 v[58:61], v[138:141], v[182:185], v[58:61]
	v_mfma_f32_16x16x32_bf16 v[54:57], v[130:133], v[190:193], v[54:57]
	v_mfma_f32_16x16x32_bf16 v[50:53], v[138:141], v[190:193], v[50:53]
	v_mfma_f32_16x16x32_bf16 v[38:41], v[130:133], v[212:215], v[38:41]
	v_mfma_f32_16x16x32_bf16 v[34:37], v[138:141], v[212:215], v[34:37]
	v_mfma_f32_16x16x32_bf16 v[22:25], v[130:133], v[220:223], v[22:25]
	v_mfma_f32_16x16x32_bf16 v[18:21], v[138:141], v[220:223], v[18:21]
	v_mfma_f32_16x16x32_bf16 v[62:65], v[134:137], v[186:189], v[62:65]
	v_mfma_f32_16x16x32_bf16 v[58:61], v[142:145], v[186:189], v[58:61]
	v_mfma_f32_16x16x32_bf16 v[54:57], v[134:137], v[208:211], v[54:57]
	v_mfma_f32_16x16x32_bf16 v[50:53], v[142:145], v[208:211], v[50:53]
	v_mfma_f32_16x16x32_bf16 v[38:41], v[134:137], v[216:219], v[38:41]
	v_mfma_f32_16x16x32_bf16 v[34:37], v[142:145], v[216:219], v[34:37]
	v_mfma_f32_16x16x32_bf16 v[22:25], v[134:137], v[240:243], v[22:25]
	v_mfma_f32_16x16x32_bf16 v[18:21], v[142:145], v[240:243], v[18:21]
	v_mfma_f32_16x16x32_bf16 v[46:49], v[158:161], v[182:185], v[46:49]
	v_mfma_f32_16x16x32_bf16 v[42:45], v[166:169], v[182:185], v[42:45]
	v_mfma_f32_16x16x32_bf16 v[30:33], v[158:161], v[190:193], v[30:33]
	v_mfma_f32_16x16x32_bf16 v[26:29], v[166:169], v[190:193], v[26:29]
	v_mfma_f32_16x16x32_bf16 v[14:17], v[158:161], v[212:215], v[14:17]
	v_mfma_f32_16x16x32_bf16 v[10:13], v[166:169], v[212:215], v[10:13]
	v_mfma_f32_16x16x32_bf16 v[6:9], v[158:161], v[220:223], v[6:9]
	v_mfma_f32_16x16x32_bf16 v[2:5], v[166:169], v[220:223], v[2:5]
	v_mfma_f32_16x16x32_bf16 v[46:49], v[162:165], v[186:189], v[46:49]
	v_mfma_f32_16x16x32_bf16 v[42:45], v[178:181], v[186:189], v[42:45]
	v_mfma_f32_16x16x32_bf16 v[30:33], v[162:165], v[208:211], v[30:33]
	v_mfma_f32_16x16x32_bf16 v[26:29], v[178:181], v[208:211], v[26:29]
	v_mfma_f32_16x16x32_bf16 v[14:17], v[162:165], v[216:219], v[14:17]
	v_mfma_f32_16x16x32_bf16 v[10:13], v[178:181], v[216:219], v[10:13]
	v_mfma_f32_16x16x32_bf16 v[6:9], v[162:165], v[240:243], v[6:9]
	v_mfma_f32_16x16x32_bf16 v[2:5], v[178:181], v[240:243], v[2:5]
	s_barrier
	s_add_i32 s19, s19, 2
	s_add_u32 s11, s11, 0x100
	s_addc_u32 s13, s13, 0
	s_add_u32 s20, s20, 0x100
	s_addc_u32 s21, s21, 0
	s_cmp_gt_u32 s19, 29
	s_cbranch_scc0 .LBB0_667
	s_and_b64 vcc, exec, s[8:9]
	s_cbranch_vccz .LBB0_670
	s_barrier
